# v71 plus: one store-drain wait removed in the P2 epilogue, nt on the fix-up phase's gate loads
# baseline (speedup 1.0000x reference)
; __device__ __forceinline__ u32x4 pack8(const float (&f)[8]) { u32x4 o; o.x = cvt_pk_bf16(f[0], f[1]); o.y = cvt_pk_bf16(f[2], f[3]); o.z = cvt_pk_bf16(f[4], f[5]); o.w = cvt_pk_bf16(f[6], f[7]); return o; }
; __device__ __forceinline__ float gelu_tanh(float x) { return x * sigmoidf_(1.5957691216057308f * (x + 0.044715f * x * x * x)); }
; __device__ __forceinline__ void fixup_phase(KP p, int l) {
;     ...
;         for (int i = 0; i < 16; ++i) {
;             const size_t m = (size_t)(m0 + i);
;             float hl[8], pc[8], gr[8], o[8], h[8];
;             unpack8(__builtin_nontemporal_load((const u32x4*)(HLOC + m * D + c0)), hl); unpack8(__builtin_nontemporal_load((const u32x4*)(PCUM + m * D + c0)), pc);
;             bf16_t* gp = P + m * DP + C_GR + c0; unpack8(*(const u32x4*)gp, gr);
; #pragma unroll
;             for (int e = 0; e < 8; ++e) { h[e] = hl[e] + pc[e] * carry[e]; o[e] = gelu_tanh(gr[e]) * h[e]; }
;             *(u32x4*)gp = pack8(o);
.Lfx_nocarry:
	s_lshl_b32 s44, s48, 11
	s_add_u32 s12, s34, 0x14a48000
	s_addc_u32 s13, s35, 0
	s_add_u32 s12, s12, s44
	s_addc_u32 s13, s13, 0
	s_add_u32 s14, s12, 0x2080000
	s_addc_u32 s15, s13, 0
	s_mul_i32 s44, s48, 0x2800
	s_add_u32 s96, s34, 0x66c9800
	s_addc_u32 s97, s35, 0
	s_add_u32 s96, s96, s44
	s_addc_u32 s97, s97, 0
	s_mov_b32 s24, s96
	s_mov_b32 s25, s97
	global_load_dwordx4 v[32:35], v26, s[12:13] nt
	global_load_dwordx4 v[36:39], v26, s[14:15] nt
	global_load_dwordx4 v[40:43], v26, s[96:97] nt
	s_add_u32 s12, s12, 0x800
	s_addc_u32 s13, s13, 0
	s_add_u32 s14, s14, 0x800
	s_addc_u32 s15, s15, 0
	s_add_u32 s96, s96, 0x2800
	s_addc_u32 s97, s97, 0
	global_load_dwordx4 v[44:47], v26, s[12:13] nt
	global_load_dwordx4 v[48:51], v26, s[14:15] nt
	global_load_dwordx4 v[52:55], v26, s[96:97] nt
	s_add_u32 s12, s12, 0x800
	s_addc_u32 s13, s13, 0
	s_add_u32 s14, s14, 0x800
	s_addc_u32 s15, s15, 0
	s_add_u32 s96, s96, 0x2800
	s_addc_u32 s97, s97, 0
	global_load_dwordx4 v[56:59], v26, s[12:13] nt
	global_load_dwordx4 v[60:63], v26, s[14:15] nt
	global_load_dwordx4 v[64:67], v26, s[96:97] nt
	s_add_u32 s12, s12, 0x800
	s_addc_u32 s13, s13, 0
	s_add_u32 s14, s14, 0x800
	s_addc_u32 s15, s15, 0
	s_add_u32 s96, s96, 0x2800
	s_addc_u32 s97, s97, 0
	global_load_dwordx4 v[68:71], v26, s[12:13] nt
	global_load_dwordx4 v[72:75], v26, s[14:15] nt
	global_load_dwordx4 v[76:79], v26, s[96:97] nt
	s_add_u32 s12, s12, 0x800
	s_addc_u32 s13, s13, 0
	s_add_u32 s14, s14, 0x800
	s_addc_u32 s15, s15, 0
	s_add_u32 s96, s96, 0x2800
	s_addc_u32 s97, s97, 0
	s_waitcnt vmcnt(9)
	v_lshlrev_b32_e32 v80, 16, v32
	v_and_b32_e32 v81, 0xffff0000, v32
	v_lshlrev_b32_e32 v82, 16, v33
	v_and_b32_e32 v83, 0xffff0000, v33
	v_lshlrev_b32_e32 v84, 16, v34
	v_and_b32_e32 v85, 0xffff0000, v34
	v_lshlrev_b32_e32 v86, 16, v35
	v_and_b32_e32 v87, 0xffff0000, v35
	v_lshlrev_b32_e32 v96, 16, v36
	v_and_b32_e32 v97, 0xffff0000, v36
	v_lshlrev_b32_e32 v98, 16, v37
	v_and_b32_e32 v99, 0xffff0000, v37
	v_lshlrev_b32_e32 v100, 16, v38
	v_and_b32_e32 v101, 0xffff0000, v38
	v_lshlrev_b32_e32 v102, 16, v39
	v_and_b32_e32 v103, 0xffff0000, v39
	v_lshlrev_b32_e32 v88, 16, v40
	v_and_b32_e32 v89, 0xffff0000, v40
	v_lshlrev_b32_e32 v90, 16, v41
	v_and_b32_e32 v91, 0xffff0000, v41
	v_lshlrev_b32_e32 v92, 16, v42
	v_and_b32_e32 v93, 0xffff0000, v42
	v_lshlrev_b32_e32 v94, 16, v43
	v_and_b32_e32 v95, 0xffff0000, v43
	v_fmac_f32_e32 v80, v96, v18
	v_fmac_f32_e32 v81, v97, v19
	v_fmac_f32_e32 v82, v98, v20
	v_fmac_f32_e32 v83, v99, v21
	v_fmac_f32_e32 v84, v100, v22
	v_fmac_f32_e32 v85, v101, v23
	v_fmac_f32_e32 v86, v102, v24
	v_fmac_f32_e32 v87, v103, v25
	v_mul_f32_e32 v104, 0x3d372713, v88
	v_mul_f32_e32 v105, 0x3d372713, v89
	v_mul_f32_e32 v106, 0x3d372713, v90
	v_mul_f32_e32 v107, 0x3d372713, v91
	v_mul_f32_e32 v108, 0x3d372713, v92
	v_mul_f32_e32 v109, 0x3d372713, v93
	v_mul_f32_e32 v110, 0x3d372713, v94
	v_mul_f32_e32 v111, 0x3d372713, v95
	v_mul_f32_e32 v104, v104, v88
	v_mul_f32_e32 v105, v105, v89
	v_mul_f32_e32 v106, v106, v90
	v_mul_f32_e32 v107, v107, v91
	v_mul_f32_e32 v108, v108, v92
	v_mul_f32_e32 v109, v109, v93
	v_mul_f32_e32 v110, v110, v94
	v_mul_f32_e32 v111, v111, v95
	v_fma_f32 v104, v104, v88, v88
	v_fma_f32 v105, v105, v89, v89
	v_fma_f32 v106, v106, v90, v90
	v_fma_f32 v107, v107, v91, v91
	v_fma_f32 v108, v108, v92, v92
	v_fma_f32 v109, v109, v93, v93
	v_fma_f32 v110, v110, v94, v94
	v_fma_f32 v111, v111, v95, v95
	v_mul_f32_e32 v104, 0x3fcc422a, v104
	v_mul_f32_e32 v105, 0x3fcc422a, v105
	v_mul_f32_e32 v106, 0x3fcc422a, v106
	v_mul_f32_e32 v107, 0x3fcc422a, v107
	v_mul_f32_e32 v108, 0x3fcc422a, v108
	v_mul_f32_e32 v109, 0x3fcc422a, v109
	v_mul_f32_e32 v110, 0x3fcc422a, v110
	v_mul_f32_e32 v111, 0x3fcc422a, v111
	v_mul_f32_e32 v104, 0xbfb8aa3b, v104
	v_mul_f32_e32 v105, 0xbfb8aa3b, v105
	v_mul_f32_e32 v106, 0xbfb8aa3b, v106
	v_mul_f32_e32 v107, 0xbfb8aa3b, v107
	v_mul_f32_e32 v108, 0xbfb8aa3b, v108
	v_mul_f32_e32 v109, 0xbfb8aa3b, v109
	v_mul_f32_e32 v110, 0xbfb8aa3b, v110
	v_mul_f32_e32 v111, 0xbfb8aa3b, v111
	v_exp_f32_e32 v104, v104
	v_exp_f32_e32 v105, v105
	v_exp_f32_e32 v106, v106
	v_exp_f32_e32 v107, v107
	v_exp_f32_e32 v108, v108
	v_exp_f32_e32 v109, v109
	v_exp_f32_e32 v110, v110
	v_exp_f32_e32 v111, v111
	v_add_f32_e32 v104, 1.0, v104
	v_add_f32_e32 v105, 1.0, v105
	v_add_f32_e32 v106, 1.0, v106
	v_add_f32_e32 v107, 1.0, v107
	v_add_f32_e32 v108, 1.0, v108
	v_add_f32_e32 v109, 1.0, v109
	v_add_f32_e32 v110, 1.0, v110
	v_add_f32_e32 v111, 1.0, v111
	v_rcp_f32_e32 v104, v104
	v_rcp_f32_e32 v105, v105
	v_rcp_f32_e32 v106, v106
	v_rcp_f32_e32 v107, v107
	v_rcp_f32_e32 v108, v108
	v_rcp_f32_e32 v109, v109
	v_rcp_f32_e32 v110, v110
	v_rcp_f32_e32 v111, v111
	v_mul_f32_e32 v104, v104, v88
	v_mul_f32_e32 v105, v105, v89
	v_mul_f32_e32 v106, v106, v90
	v_mul_f32_e32 v107, v107, v91
	v_mul_f32_e32 v108, v108, v92
	v_mul_f32_e32 v109, v109, v93
	v_mul_f32_e32 v110, v110, v94
	v_mul_f32_e32 v111, v111, v95
	v_mul_f32_e32 v104, v80, v104
	v_mul_f32_e32 v105, v81, v105
	v_mul_f32_e32 v106, v82, v106
	v_mul_f32_e32 v107, v83, v107
	v_mul_f32_e32 v108, v84, v108
	v_mul_f32_e32 v109, v85, v109
	v_mul_f32_e32 v110, v86, v110
	v_mul_f32_e32 v111, v87, v111
	v_cvt_pk_bf16_f32 v112, v104, v105
	v_cvt_pk_bf16_f32 v113, v106, v107
	v_cvt_pk_bf16_f32 v114, v108, v109
	v_cvt_pk_bf16_f32 v115, v110, v111
	global_store_dwordx4 v27, v[112:115], s[24:25]
	s_add_u32 s24, s24, 0x2800
	s_addc_u32 s25, s25, 0
	global_load_dwordx4 v[32:35], v26, s[12:13] nt
	global_load_dwordx4 v[36:39], v26, s[14:15] nt
	global_load_dwordx4 v[40:43], v26, s[96:97] nt
	s_add_u32 s12, s12, 0x800
	s_addc_u32 s13, s13, 0
	s_add_u32 s14, s14, 0x800
	s_addc_u32 s15, s15, 0
	s_add_u32 s96, s96, 0x2800
	s_addc_u32 s97, s97, 0
	s_waitcnt vmcnt(10)
; __device__ __forceinline__ u32x4 pack8(const float (&f)[8]) { u32x4 o; o.x = cvt_pk_bf16(f[0], f[1]); o.y = cvt_pk_bf16(f[2], f[3]); o.z = cvt_pk_bf16(f[4], f[5]); o.w = cvt_pk_bf16(f[6], f[7]); return o; }
; __device__ __forceinline__ float gelu_tanh(float x) { return x * sigmoidf_(1.5957691216057308f * (x + 0.044715f * x * x * x)); }
; __device__ __forceinline__ void fixup_phase(KP p, int l) {
;     ...
;         for (int i = 0; i < 16; ++i) {
;             const size_t m = (size_t)(m0 + i);
;             float hl[8], pc[8], gr[8], o[8], h[8];
;             unpack8(__builtin_nontemporal_load((const u32x4*)(HLOC + m * D + c0)), hl); unpack8(__builtin_nontemporal_load((const u32x4*)(PCUM + m * D + c0)), pc);
;             bf16_t* gp = P + m * DP + C_GR + c0; unpack8(*(const u32x4*)gp, gr);
; #pragma unroll
;             for (int e = 0; e < 8; ++e) { h[e] = hl[e] + pc[e] * carry[e]; o[e] = gelu_tanh(gr[e]) * h[e]; }
;             *(u32x4*)gp = pack8(o);
	v_lshlrev_b32_e32 v80, 16, v44
	v_and_b32_e32 v81, 0xffff0000, v44
	v_lshlrev_b32_e32 v82, 16, v45
	v_and_b32_e32 v83, 0xffff0000, v45
	v_lshlrev_b32_e32 v84, 16, v46
	v_and_b32_e32 v85, 0xffff0000, v46
	v_lshlrev_b32_e32 v86, 16, v47
	v_and_b32_e32 v87, 0xffff0000, v47
	v_lshlrev_b32_e32 v96, 16, v48
	v_and_b32_e32 v97, 0xffff0000, v48
	v_lshlrev_b32_e32 v98, 16, v49
	v_and_b32_e32 v99, 0xffff0000, v49
	v_lshlrev_b32_e32 v100, 16, v50
	v_and_b32_e32 v101, 0xffff0000, v50
	v_lshlrev_b32_e32 v102, 16, v51
	v_and_b32_e32 v103, 0xffff0000, v51
	v_lshlrev_b32_e32 v88, 16, v52
	v_and_b32_e32 v89, 0xffff0000, v52
	v_lshlrev_b32_e32 v90, 16, v53
	v_and_b32_e32 v91, 0xffff0000, v53
	v_lshlrev_b32_e32 v92, 16, v54
	v_and_b32_e32 v93, 0xffff0000, v54
	v_lshlrev_b32_e32 v94, 16, v55
	v_and_b32_e32 v95, 0xffff0000, v55
	v_fmac_f32_e32 v80, v96, v18
	v_fmac_f32_e32 v81, v97, v19
	v_fmac_f32_e32 v82, v98, v20
	v_fmac_f32_e32 v83, v99, v21
	v_fmac_f32_e32 v84, v100, v22
	v_fmac_f32_e32 v85, v101, v23
	v_fmac_f32_e32 v86, v102, v24
	v_fmac_f32_e32 v87, v103, v25
	v_mul_f32_e32 v104, 0x3d372713, v88
	v_mul_f32_e32 v105, 0x3d372713, v89
	v_mul_f32_e32 v106, 0x3d372713, v90
	v_mul_f32_e32 v107, 0x3d372713, v91
	v_mul_f32_e32 v108, 0x3d372713, v92
	v_mul_f32_e32 v109, 0x3d372713, v93
	v_mul_f32_e32 v110, 0x3d372713, v94
	v_mul_f32_e32 v111, 0x3d372713, v95
	v_mul_f32_e32 v104, v104, v88
	v_mul_f32_e32 v105, v105, v89
	v_mul_f32_e32 v106, v106, v90
	v_mul_f32_e32 v107, v107, v91
	v_mul_f32_e32 v108, v108, v92
	v_mul_f32_e32 v109, v109, v93
	v_mul_f32_e32 v110, v110, v94
	v_mul_f32_e32 v111, v111, v95
	v_fma_f32 v104, v104, v88, v88
	v_fma_f32 v105, v105, v89, v89
	v_fma_f32 v106, v106, v90, v90
	v_fma_f32 v107, v107, v91, v91
	v_fma_f32 v108, v108, v92, v92
	v_fma_f32 v109, v109, v93, v93
	v_fma_f32 v110, v110, v94, v94
	v_fma_f32 v111, v111, v95, v95
	v_mul_f32_e32 v104, 0x3fcc422a, v104
	v_mul_f32_e32 v105, 0x3fcc422a, v105
	v_mul_f32_e32 v106, 0x3fcc422a, v106
	v_mul_f32_e32 v107, 0x3fcc422a, v107
	v_mul_f32_e32 v108, 0x3fcc422a, v108
	v_mul_f32_e32 v109, 0x3fcc422a, v109
	v_mul_f32_e32 v110, 0x3fcc422a, v110
	v_mul_f32_e32 v111, 0x3fcc422a, v111
	v_mul_f32_e32 v104, 0xbfb8aa3b, v104
	v_mul_f32_e32 v105, 0xbfb8aa3b, v105
	v_mul_f32_e32 v106, 0xbfb8aa3b, v106
	v_mul_f32_e32 v107, 0xbfb8aa3b, v107
	v_mul_f32_e32 v108, 0xbfb8aa3b, v108
	v_mul_f32_e32 v109, 0xbfb8aa3b, v109
	v_mul_f32_e32 v110, 0xbfb8aa3b, v110
	v_mul_f32_e32 v111, 0xbfb8aa3b, v111
	v_exp_f32_e32 v104, v104
	v_exp_f32_e32 v105, v105
	v_exp_f32_e32 v106, v106
	v_exp_f32_e32 v107, v107
	v_exp_f32_e32 v108, v108
	v_exp_f32_e32 v109, v109
	v_exp_f32_e32 v110, v110
	v_exp_f32_e32 v111, v111
	v_add_f32_e32 v104, 1.0, v104
	v_add_f32_e32 v105, 1.0, v105
	v_add_f32_e32 v106, 1.0, v106
	v_add_f32_e32 v107, 1.0, v107
	v_add_f32_e32 v108, 1.0, v108
	v_add_f32_e32 v109, 1.0, v109
	v_add_f32_e32 v110, 1.0, v110
	v_add_f32_e32 v111, 1.0, v111
	v_rcp_f32_e32 v104, v104
	v_rcp_f32_e32 v105, v105
	v_rcp_f32_e32 v106, v106
	v_rcp_f32_e32 v107, v107
	v_rcp_f32_e32 v108, v108
	v_rcp_f32_e32 v109, v109
	v_rcp_f32_e32 v110, v110
	v_rcp_f32_e32 v111, v111
	v_mul_f32_e32 v104, v104, v88
	v_mul_f32_e32 v105, v105, v89
	v_mul_f32_e32 v106, v106, v90
	v_mul_f32_e32 v107, v107, v91
	v_mul_f32_e32 v108, v108, v92
	v_mul_f32_e32 v109, v109, v93
	v_mul_f32_e32 v110, v110, v94
	v_mul_f32_e32 v111, v111, v95
	v_mul_f32_e32 v104, v80, v104
	v_mul_f32_e32 v105, v81, v105
	v_mul_f32_e32 v106, v82, v106
	v_mul_f32_e32 v107, v83, v107
	v_mul_f32_e32 v108, v84, v108
	v_mul_f32_e32 v109, v85, v109
	v_mul_f32_e32 v110, v86, v110
	v_mul_f32_e32 v111, v87, v111
	v_cvt_pk_bf16_f32 v112, v104, v105
	v_cvt_pk_bf16_f32 v113, v106, v107
	v_cvt_pk_bf16_f32 v114, v108, v109
	v_cvt_pk_bf16_f32 v115, v110, v111
	global_store_dwordx4 v27, v[112:115], s[24:25]
	s_add_u32 s24, s24, 0x2800
	s_addc_u32 s25, s25, 0
	global_load_dwordx4 v[44:47], v26, s[12:13] nt
	global_load_dwordx4 v[48:51], v26, s[14:15] nt
	global_load_dwordx4 v[52:55], v26, s[96:97] nt
	s_add_u32 s12, s12, 0x800
	s_addc_u32 s13, s13, 0
	s_add_u32 s14, s14, 0x800
	s_addc_u32 s15, s15, 0
	s_add_u32 s96, s96, 0x2800
	s_addc_u32 s97, s97, 0
	s_waitcnt vmcnt(11)
	v_lshlrev_b32_e32 v80, 16, v56
	v_and_b32_e32 v81, 0xffff0000, v56
	v_lshlrev_b32_e32 v82, 16, v57
	v_and_b32_e32 v83, 0xffff0000, v57
	v_lshlrev_b32_e32 v84, 16, v58
	v_and_b32_e32 v85, 0xffff0000, v58
	v_lshlrev_b32_e32 v86, 16, v59
	v_and_b32_e32 v87, 0xffff0000, v59
	v_lshlrev_b32_e32 v96, 16, v60
	v_and_b32_e32 v97, 0xffff0000, v60
	v_lshlrev_b32_e32 v98, 16, v61
	v_and_b32_e32 v99, 0xffff0000, v61
	v_lshlrev_b32_e32 v100, 16, v62
	v_and_b32_e32 v101, 0xffff0000, v62
	v_lshlrev_b32_e32 v102, 16, v63
	v_and_b32_e32 v103, 0xffff0000, v63
	v_lshlrev_b32_e32 v88, 16, v64
	v_and_b32_e32 v89, 0xffff0000, v64
	v_lshlrev_b32_e32 v90, 16, v65
	v_and_b32_e32 v91, 0xffff0000, v65
	v_lshlrev_b32_e32 v92, 16, v66
	v_and_b32_e32 v93, 0xffff0000, v66
	v_lshlrev_b32_e32 v94, 16, v67
	v_and_b32_e32 v95, 0xffff0000, v67
	v_fmac_f32_e32 v80, v96, v18
	v_fmac_f32_e32 v81, v97, v19
	v_fmac_f32_e32 v82, v98, v20
	v_fmac_f32_e32 v83, v99, v21
	v_fmac_f32_e32 v84, v100, v22
	v_fmac_f32_e32 v85, v101, v23
	v_fmac_f32_e32 v86, v102, v24
	v_fmac_f32_e32 v87, v103, v25
	v_mul_f32_e32 v104, 0x3d372713, v88
	v_mul_f32_e32 v105, 0x3d372713, v89
	v_mul_f32_e32 v106, 0x3d372713, v90
	v_mul_f32_e32 v107, 0x3d372713, v91
	v_mul_f32_e32 v108, 0x3d372713, v92
	v_mul_f32_e32 v109, 0x3d372713, v93
	v_mul_f32_e32 v110, 0x3d372713, v94
	v_mul_f32_e32 v111, 0x3d372713, v95
	v_mul_f32_e32 v104, v104, v88
	v_mul_f32_e32 v105, v105, v89
	v_mul_f32_e32 v106, v106, v90
; __device__ __forceinline__ u32x4 pack8(const float (&f)[8]) { u32x4 o; o.x = cvt_pk_bf16(f[0], f[1]); o.y = cvt_pk_bf16(f[2], f[3]); o.z = cvt_pk_bf16(f[4], f[5]); o.w = cvt_pk_bf16(f[6], f[7]); return o; }
; __device__ __forceinline__ float gelu_tanh(float x) { return x * sigmoidf_(1.5957691216057308f * (x + 0.044715f * x * x * x)); }
; __device__ __forceinline__ void fixup_phase(KP p, int l) {
;     ...
;         for (int i = 0; i < 16; ++i) {
;             const size_t m = (size_t)(m0 + i);
;             float hl[8], pc[8], gr[8], o[8], h[8];
;             unpack8(__builtin_nontemporal_load((const u32x4*)(HLOC + m * D + c0)), hl); unpack8(__builtin_nontemporal_load((const u32x4*)(PCUM + m * D + c0)), pc);
;             bf16_t* gp = P + m * DP + C_GR + c0; unpack8(*(const u32x4*)gp, gr);
; #pragma unroll
;             for (int e = 0; e < 8; ++e) { h[e] = hl[e] + pc[e] * carry[e]; o[e] = gelu_tanh(gr[e]) * h[e]; }
;             *(u32x4*)gp = pack8(o);
	v_mul_f32_e32 v107, v107, v91
	v_mul_f32_e32 v108, v108, v92
	v_mul_f32_e32 v109, v109, v93
	v_mul_f32_e32 v110, v110, v94
	v_mul_f32_e32 v111, v111, v95
	v_fma_f32 v104, v104, v88, v88
	v_fma_f32 v105, v105, v89, v89
	v_fma_f32 v106, v106, v90, v90
	v_fma_f32 v107, v107, v91, v91
	v_fma_f32 v108, v108, v92, v92
	v_fma_f32 v109, v109, v93, v93
	v_fma_f32 v110, v110, v94, v94
	v_fma_f32 v111, v111, v95, v95
	v_mul_f32_e32 v104, 0x3fcc422a, v104
	v_mul_f32_e32 v105, 0x3fcc422a, v105
	v_mul_f32_e32 v106, 0x3fcc422a, v106
	v_mul_f32_e32 v107, 0x3fcc422a, v107
	v_mul_f32_e32 v108, 0x3fcc422a, v108
	v_mul_f32_e32 v109, 0x3fcc422a, v109
	v_mul_f32_e32 v110, 0x3fcc422a, v110
	v_mul_f32_e32 v111, 0x3fcc422a, v111
	v_mul_f32_e32 v104, 0xbfb8aa3b, v104
	v_mul_f32_e32 v105, 0xbfb8aa3b, v105
	v_mul_f32_e32 v106, 0xbfb8aa3b, v106
	v_mul_f32_e32 v107, 0xbfb8aa3b, v107
	v_mul_f32_e32 v108, 0xbfb8aa3b, v108
	v_mul_f32_e32 v109, 0xbfb8aa3b, v109
	v_mul_f32_e32 v110, 0xbfb8aa3b, v110
	v_mul_f32_e32 v111, 0xbfb8aa3b, v111
	v_exp_f32_e32 v104, v104
	v_exp_f32_e32 v105, v105
	v_exp_f32_e32 v106, v106
	v_exp_f32_e32 v107, v107
	v_exp_f32_e32 v108, v108
	v_exp_f32_e32 v109, v109
	v_exp_f32_e32 v110, v110
	v_exp_f32_e32 v111, v111
	v_add_f32_e32 v104, 1.0, v104
	v_add_f32_e32 v105, 1.0, v105
	v_add_f32_e32 v106, 1.0, v106
	v_add_f32_e32 v107, 1.0, v107
	v_add_f32_e32 v108, 1.0, v108
	v_add_f32_e32 v109, 1.0, v109
	v_add_f32_e32 v110, 1.0, v110
	v_add_f32_e32 v111, 1.0, v111
	v_rcp_f32_e32 v104, v104
	v_rcp_f32_e32 v105, v105
	v_rcp_f32_e32 v106, v106
	v_rcp_f32_e32 v107, v107
	v_rcp_f32_e32 v108, v108
	v_rcp_f32_e32 v109, v109
	v_rcp_f32_e32 v110, v110
	v_rcp_f32_e32 v111, v111
	v_mul_f32_e32 v104, v104, v88
	v_mul_f32_e32 v105, v105, v89
	v_mul_f32_e32 v106, v106, v90
	v_mul_f32_e32 v107, v107, v91
	v_mul_f32_e32 v108, v108, v92
	v_mul_f32_e32 v109, v109, v93
	v_mul_f32_e32 v110, v110, v94
	v_mul_f32_e32 v111, v111, v95
	v_mul_f32_e32 v104, v80, v104
	v_mul_f32_e32 v105, v81, v105
	v_mul_f32_e32 v106, v82, v106
	v_mul_f32_e32 v107, v83, v107
	v_mul_f32_e32 v108, v84, v108
	v_mul_f32_e32 v109, v85, v109
	v_mul_f32_e32 v110, v86, v110
	v_mul_f32_e32 v111, v87, v111
	v_cvt_pk_bf16_f32 v112, v104, v105
	v_cvt_pk_bf16_f32 v113, v106, v107
	v_cvt_pk_bf16_f32 v114, v108, v109
	v_cvt_pk_bf16_f32 v115, v110, v111
	global_store_dwordx4 v27, v[112:115], s[24:25]
	s_add_u32 s24, s24, 0x2800
	s_addc_u32 s25, s25, 0
	global_load_dwordx4 v[56:59], v26, s[12:13] nt
	global_load_dwordx4 v[60:63], v26, s[14:15] nt
	global_load_dwordx4 v[64:67], v26, s[96:97] nt
	s_add_u32 s12, s12, 0x800
	s_addc_u32 s13, s13, 0
	s_add_u32 s14, s14, 0x800
	s_addc_u32 s15, s15, 0
	s_add_u32 s96, s96, 0x2800
	s_addc_u32 s97, s97, 0
	s_waitcnt vmcnt(12)
	v_lshlrev_b32_e32 v80, 16, v68
	v_and_b32_e32 v81, 0xffff0000, v68
	v_lshlrev_b32_e32 v82, 16, v69
	v_and_b32_e32 v83, 0xffff0000, v69
	v_lshlrev_b32_e32 v84, 16, v70
	v_and_b32_e32 v85, 0xffff0000, v70
	v_lshlrev_b32_e32 v86, 16, v71
	v_and_b32_e32 v87, 0xffff0000, v71
	v_lshlrev_b32_e32 v96, 16, v72
	v_and_b32_e32 v97, 0xffff0000, v72
	v_lshlrev_b32_e32 v98, 16, v73
	v_and_b32_e32 v99, 0xffff0000, v73
	v_lshlrev_b32_e32 v100, 16, v74
	v_and_b32_e32 v101, 0xffff0000, v74
	v_lshlrev_b32_e32 v102, 16, v75
	v_and_b32_e32 v103, 0xffff0000, v75
	v_lshlrev_b32_e32 v88, 16, v76
	v_and_b32_e32 v89, 0xffff0000, v76
	v_lshlrev_b32_e32 v90, 16, v77
	v_and_b32_e32 v91, 0xffff0000, v77
	v_lshlrev_b32_e32 v92, 16, v78
	v_and_b32_e32 v93, 0xffff0000, v78
	v_lshlrev_b32_e32 v94, 16, v79
	v_and_b32_e32 v95, 0xffff0000, v79
	v_fmac_f32_e32 v80, v96, v18
	v_fmac_f32_e32 v81, v97, v19
	v_fmac_f32_e32 v82, v98, v20
	v_fmac_f32_e32 v83, v99, v21
	v_fmac_f32_e32 v84, v100, v22
	v_fmac_f32_e32 v85, v101, v23
	v_fmac_f32_e32 v86, v102, v24
	v_fmac_f32_e32 v87, v103, v25
	v_mul_f32_e32 v104, 0x3d372713, v88
	v_mul_f32_e32 v105, 0x3d372713, v89
	v_mul_f32_e32 v106, 0x3d372713, v90
	v_mul_f32_e32 v107, 0x3d372713, v91
	v_mul_f32_e32 v108, 0x3d372713, v92
	v_mul_f32_e32 v109, 0x3d372713, v93
	v_mul_f32_e32 v110, 0x3d372713, v94
	v_mul_f32_e32 v111, 0x3d372713, v95
	v_mul_f32_e32 v104, v104, v88
	v_mul_f32_e32 v105, v105, v89
	v_mul_f32_e32 v106, v106, v90
	v_mul_f32_e32 v107, v107, v91
	v_mul_f32_e32 v108, v108, v92
	v_mul_f32_e32 v109, v109, v93
	v_mul_f32_e32 v110, v110, v94
	v_mul_f32_e32 v111, v111, v95
	v_fma_f32 v104, v104, v88, v88
	v_fma_f32 v105, v105, v89, v89
	v_fma_f32 v106, v106, v90, v90
	v_fma_f32 v107, v107, v91, v91
	v_fma_f32 v108, v108, v92, v92
	v_fma_f32 v109, v109, v93, v93
	v_fma_f32 v110, v110, v94, v94
	v_fma_f32 v111, v111, v95, v95
	v_mul_f32_e32 v104, 0x3fcc422a, v104
	v_mul_f32_e32 v105, 0x3fcc422a, v105
	v_mul_f32_e32 v106, 0x3fcc422a, v106
	v_mul_f32_e32 v107, 0x3fcc422a, v107
	v_mul_f32_e32 v108, 0x3fcc422a, v108
	v_mul_f32_e32 v109, 0x3fcc422a, v109
	v_mul_f32_e32 v110, 0x3fcc422a, v110
	v_mul_f32_e32 v111, 0x3fcc422a, v111
	v_mul_f32_e32 v104, 0xbfb8aa3b, v104
	v_mul_f32_e32 v105, 0xbfb8aa3b, v105
	v_mul_f32_e32 v106, 0xbfb8aa3b, v106
	v_mul_f32_e32 v107, 0xbfb8aa3b, v107
	v_mul_f32_e32 v108, 0xbfb8aa3b, v108
	v_mul_f32_e32 v109, 0xbfb8aa3b, v109
	v_mul_f32_e32 v110, 0xbfb8aa3b, v110
	v_mul_f32_e32 v111, 0xbfb8aa3b, v111
	v_exp_f32_e32 v104, v104
	v_exp_f32_e32 v105, v105
	v_exp_f32_e32 v106, v106
	v_exp_f32_e32 v107, v107
	v_exp_f32_e32 v108, v108
	v_exp_f32_e32 v109, v109
	v_exp_f32_e32 v110, v110
	v_exp_f32_e32 v111, v111
	v_add_f32_e32 v104, 1.0, v104
	v_add_f32_e32 v105, 1.0, v105
	v_add_f32_e32 v106, 1.0, v106
	v_add_f32_e32 v107, 1.0, v107
	v_add_f32_e32 v108, 1.0, v108
	v_add_f32_e32 v109, 1.0, v109
	v_add_f32_e32 v110, 1.0, v110
	v_add_f32_e32 v111, 1.0, v111
	v_rcp_f32_e32 v104, v104
	v_rcp_f32_e32 v105, v105
	v_rcp_f32_e32 v106, v106
	v_rcp_f32_e32 v107, v107
	v_rcp_f32_e32 v108, v108
	v_rcp_f32_e32 v109, v109
	v_rcp_f32_e32 v110, v110
	v_rcp_f32_e32 v111, v111
	v_mul_f32_e32 v104, v104, v88
	v_mul_f32_e32 v105, v105, v89
	v_mul_f32_e32 v106, v106, v90
	v_mul_f32_e32 v107, v107, v91
	v_mul_f32_e32 v108, v108, v92
	v_mul_f32_e32 v109, v109, v93
	v_mul_f32_e32 v110, v110, v94
	v_mul_f32_e32 v111, v111, v95
	v_mul_f32_e32 v104, v80, v104
	v_mul_f32_e32 v105, v81, v105
	v_mul_f32_e32 v106, v82, v106
	v_mul_f32_e32 v107, v83, v107
	v_mul_f32_e32 v108, v84, v108
	v_mul_f32_e32 v109, v85, v109
	v_mul_f32_e32 v110, v86, v110
	v_mul_f32_e32 v111, v87, v111
	v_cvt_pk_bf16_f32 v112, v104, v105
	v_cvt_pk_bf16_f32 v113, v106, v107
	v_cvt_pk_bf16_f32 v114, v108, v109
	v_cvt_pk_bf16_f32 v115, v110, v111
	global_store_dwordx4 v27, v[112:115], s[24:25]
	s_add_u32 s24, s24, 0x2800
	s_addc_u32 s25, s25, 0
	global_load_dwordx4 v[68:71], v26, s[12:13] nt
	global_load_dwordx4 v[72:75], v26, s[14:15] nt
	global_load_dwordx4 v[76:79], v26, s[96:97] nt
	s_add_u32 s12, s12, 0x800
	s_addc_u32 s13, s13, 0
	s_add_u32 s14, s14, 0x800
	s_addc_u32 s15, s15, 0
	s_add_u32 s96, s96, 0x2800
	s_addc_u32 s97, s97, 0
	s_waitcnt vmcnt(12)
; __device__ __forceinline__ u32x4 pack8(const float (&f)[8]) { u32x4 o; o.x = cvt_pk_bf16(f[0], f[1]); o.y = cvt_pk_bf16(f[2], f[3]); o.z = cvt_pk_bf16(f[4], f[5]); o.w = cvt_pk_bf16(f[6], f[7]); return o; }
; __device__ __forceinline__ float gelu_tanh(float x) { return x * sigmoidf_(1.5957691216057308f * (x + 0.044715f * x * x * x)); }
; __device__ __forceinline__ void fixup_phase(KP p, int l) {
;     ...
;         for (int i = 0; i < 16; ++i) {
;             const size_t m = (size_t)(m0 + i);
;             float hl[8], pc[8], gr[8], o[8], h[8];
;             unpack8(__builtin_nontemporal_load((const u32x4*)(HLOC + m * D + c0)), hl); unpack8(__builtin_nontemporal_load((const u32x4*)(PCUM + m * D + c0)), pc);
;             bf16_t* gp = P + m * DP + C_GR + c0; unpack8(*(const u32x4*)gp, gr);
; #pragma unroll
;             for (int e = 0; e < 8; ++e) { h[e] = hl[e] + pc[e] * carry[e]; o[e] = gelu_tanh(gr[e]) * h[e]; }
;             *(u32x4*)gp = pack8(o);
	v_lshlrev_b32_e32 v80, 16, v32
	v_and_b32_e32 v81, 0xffff0000, v32
	v_lshlrev_b32_e32 v82, 16, v33
	v_and_b32_e32 v83, 0xffff0000, v33
	v_lshlrev_b32_e32 v84, 16, v34
	v_and_b32_e32 v85, 0xffff0000, v34
	v_lshlrev_b32_e32 v86, 16, v35
	v_and_b32_e32 v87, 0xffff0000, v35
	v_lshlrev_b32_e32 v96, 16, v36
	v_and_b32_e32 v97, 0xffff0000, v36
	v_lshlrev_b32_e32 v98, 16, v37
	v_and_b32_e32 v99, 0xffff0000, v37
	v_lshlrev_b32_e32 v100, 16, v38
	v_and_b32_e32 v101, 0xffff0000, v38
	v_lshlrev_b32_e32 v102, 16, v39
	v_and_b32_e32 v103, 0xffff0000, v39
	v_lshlrev_b32_e32 v88, 16, v40
	v_and_b32_e32 v89, 0xffff0000, v40
	v_lshlrev_b32_e32 v90, 16, v41
	v_and_b32_e32 v91, 0xffff0000, v41
	v_lshlrev_b32_e32 v92, 16, v42
	v_and_b32_e32 v93, 0xffff0000, v42
	v_lshlrev_b32_e32 v94, 16, v43
	v_and_b32_e32 v95, 0xffff0000, v43
	v_fmac_f32_e32 v80, v96, v18
	v_fmac_f32_e32 v81, v97, v19
	v_fmac_f32_e32 v82, v98, v20
	v_fmac_f32_e32 v83, v99, v21
	v_fmac_f32_e32 v84, v100, v22
	v_fmac_f32_e32 v85, v101, v23
	v_fmac_f32_e32 v86, v102, v24
	v_fmac_f32_e32 v87, v103, v25
	v_mul_f32_e32 v104, 0x3d372713, v88
	v_mul_f32_e32 v105, 0x3d372713, v89
	v_mul_f32_e32 v106, 0x3d372713, v90
	v_mul_f32_e32 v107, 0x3d372713, v91
	v_mul_f32_e32 v108, 0x3d372713, v92
	v_mul_f32_e32 v109, 0x3d372713, v93
	v_mul_f32_e32 v110, 0x3d372713, v94
	v_mul_f32_e32 v111, 0x3d372713, v95
	v_mul_f32_e32 v104, v104, v88
	v_mul_f32_e32 v105, v105, v89
	v_mul_f32_e32 v106, v106, v90
	v_mul_f32_e32 v107, v107, v91
	v_mul_f32_e32 v108, v108, v92
	v_mul_f32_e32 v109, v109, v93
	v_mul_f32_e32 v110, v110, v94
	v_mul_f32_e32 v111, v111, v95
	v_fma_f32 v104, v104, v88, v88
	v_fma_f32 v105, v105, v89, v89
	v_fma_f32 v106, v106, v90, v90
	v_fma_f32 v107, v107, v91, v91
	v_fma_f32 v108, v108, v92, v92
	v_fma_f32 v109, v109, v93, v93
	v_fma_f32 v110, v110, v94, v94
	v_fma_f32 v111, v111, v95, v95
	v_mul_f32_e32 v104, 0x3fcc422a, v104
	v_mul_f32_e32 v105, 0x3fcc422a, v105
	v_mul_f32_e32 v106, 0x3fcc422a, v106
	v_mul_f32_e32 v107, 0x3fcc422a, v107
	v_mul_f32_e32 v108, 0x3fcc422a, v108
	v_mul_f32_e32 v109, 0x3fcc422a, v109
	v_mul_f32_e32 v110, 0x3fcc422a, v110
	v_mul_f32_e32 v111, 0x3fcc422a, v111
	v_mul_f32_e32 v104, 0xbfb8aa3b, v104
	v_mul_f32_e32 v105, 0xbfb8aa3b, v105
	v_mul_f32_e32 v106, 0xbfb8aa3b, v106
	v_mul_f32_e32 v107, 0xbfb8aa3b, v107
	v_mul_f32_e32 v108, 0xbfb8aa3b, v108
	v_mul_f32_e32 v109, 0xbfb8aa3b, v109
	v_mul_f32_e32 v110, 0xbfb8aa3b, v110
	v_mul_f32_e32 v111, 0xbfb8aa3b, v111
	v_exp_f32_e32 v104, v104
	v_exp_f32_e32 v105, v105
	v_exp_f32_e32 v106, v106
	v_exp_f32_e32 v107, v107
	v_exp_f32_e32 v108, v108
	v_exp_f32_e32 v109, v109
	v_exp_f32_e32 v110, v110
	v_exp_f32_e32 v111, v111
	v_add_f32_e32 v104, 1.0, v104
	v_add_f32_e32 v105, 1.0, v105
	v_add_f32_e32 v106, 1.0, v106
	v_add_f32_e32 v107, 1.0, v107
	v_add_f32_e32 v108, 1.0, v108
	v_add_f32_e32 v109, 1.0, v109
	v_add_f32_e32 v110, 1.0, v110
	v_add_f32_e32 v111, 1.0, v111
	v_rcp_f32_e32 v104, v104
	v_rcp_f32_e32 v105, v105
	v_rcp_f32_e32 v106, v106
	v_rcp_f32_e32 v107, v107
	v_rcp_f32_e32 v108, v108
	v_rcp_f32_e32 v109, v109
	v_rcp_f32_e32 v110, v110
	v_rcp_f32_e32 v111, v111
	v_mul_f32_e32 v104, v104, v88
	v_mul_f32_e32 v105, v105, v89
	v_mul_f32_e32 v106, v106, v90
	v_mul_f32_e32 v107, v107, v91
	v_mul_f32_e32 v108, v108, v92
	v_mul_f32_e32 v109, v109, v93
	v_mul_f32_e32 v110, v110, v94
	v_mul_f32_e32 v111, v111, v95
	v_mul_f32_e32 v104, v80, v104
	v_mul_f32_e32 v105, v81, v105
	v_mul_f32_e32 v106, v82, v106
	v_mul_f32_e32 v107, v83, v107
	v_mul_f32_e32 v108, v84, v108
	v_mul_f32_e32 v109, v85, v109
	v_mul_f32_e32 v110, v86, v110
	v_mul_f32_e32 v111, v87, v111
	v_cvt_pk_bf16_f32 v112, v104, v105
	v_cvt_pk_bf16_f32 v113, v106, v107
	v_cvt_pk_bf16_f32 v114, v108, v109
	v_cvt_pk_bf16_f32 v115, v110, v111
	global_store_dwordx4 v27, v[112:115], s[24:25]
	s_add_u32 s24, s24, 0x2800
	s_addc_u32 s25, s25, 0
	global_load_dwordx4 v[32:35], v26, s[12:13] nt
	global_load_dwordx4 v[36:39], v26, s[14:15] nt
	global_load_dwordx4 v[40:43], v26, s[96:97] nt
	s_add_u32 s12, s12, 0x800
	s_addc_u32 s13, s13, 0
	s_add_u32 s14, s14, 0x800
	s_addc_u32 s15, s15, 0
	s_add_u32 s96, s96, 0x2800
	s_addc_u32 s97, s97, 0
	s_waitcnt vmcnt(12)
	v_lshlrev_b32_e32 v80, 16, v44
	v_and_b32_e32 v81, 0xffff0000, v44
	v_lshlrev_b32_e32 v82, 16, v45
	v_and_b32_e32 v83, 0xffff0000, v45
	v_lshlrev_b32_e32 v84, 16, v46
	v_and_b32_e32 v85, 0xffff0000, v46
	v_lshlrev_b32_e32 v86, 16, v47
	v_and_b32_e32 v87, 0xffff0000, v47
	v_lshlrev_b32_e32 v96, 16, v48
	v_and_b32_e32 v97, 0xffff0000, v48
	v_lshlrev_b32_e32 v98, 16, v49
	v_and_b32_e32 v99, 0xffff0000, v49
	v_lshlrev_b32_e32 v100, 16, v50
	v_and_b32_e32 v101, 0xffff0000, v50
	v_lshlrev_b32_e32 v102, 16, v51
	v_and_b32_e32 v103, 0xffff0000, v51
	v_lshlrev_b32_e32 v88, 16, v52
	v_and_b32_e32 v89, 0xffff0000, v52
	v_lshlrev_b32_e32 v90, 16, v53
	v_and_b32_e32 v91, 0xffff0000, v53
	v_lshlrev_b32_e32 v92, 16, v54
	v_and_b32_e32 v93, 0xffff0000, v54
	v_lshlrev_b32_e32 v94, 16, v55
	v_and_b32_e32 v95, 0xffff0000, v55
	v_fmac_f32_e32 v80, v96, v18
	v_fmac_f32_e32 v81, v97, v19
	v_fmac_f32_e32 v82, v98, v20
	v_fmac_f32_e32 v83, v99, v21
	v_fmac_f32_e32 v84, v100, v22
	v_fmac_f32_e32 v85, v101, v23
	v_fmac_f32_e32 v86, v102, v24
	v_fmac_f32_e32 v87, v103, v25
	v_mul_f32_e32 v104, 0x3d372713, v88
	v_mul_f32_e32 v105, 0x3d372713, v89
	v_mul_f32_e32 v106, 0x3d372713, v90
	v_mul_f32_e32 v107, 0x3d372713, v91
	v_mul_f32_e32 v108, 0x3d372713, v92
	v_mul_f32_e32 v109, 0x3d372713, v93
	v_mul_f32_e32 v110, 0x3d372713, v94
	v_mul_f32_e32 v111, 0x3d372713, v95
	v_mul_f32_e32 v104, v104, v88
	v_mul_f32_e32 v105, v105, v89
	v_mul_f32_e32 v106, v106, v90
; __device__ __forceinline__ u32x4 pack8(const float (&f)[8]) { u32x4 o; o.x = cvt_pk_bf16(f[0], f[1]); o.y = cvt_pk_bf16(f[2], f[3]); o.z = cvt_pk_bf16(f[4], f[5]); o.w = cvt_pk_bf16(f[6], f[7]); return o; }
; __device__ __forceinline__ float gelu_tanh(float x) { return x * sigmoidf_(1.5957691216057308f * (x + 0.044715f * x * x * x)); }
; __device__ __forceinline__ void fixup_phase(KP p, int l) {
;     ...
;         for (int i = 0; i < 16; ++i) {
;             const size_t m = (size_t)(m0 + i);
;             float hl[8], pc[8], gr[8], o[8], h[8];
;             unpack8(__builtin_nontemporal_load((const u32x4*)(HLOC + m * D + c0)), hl); unpack8(__builtin_nontemporal_load((const u32x4*)(PCUM + m * D + c0)), pc);
;             bf16_t* gp = P + m * DP + C_GR + c0; unpack8(*(const u32x4*)gp, gr);
; #pragma unroll
;             for (int e = 0; e < 8; ++e) { h[e] = hl[e] + pc[e] * carry[e]; o[e] = gelu_tanh(gr[e]) * h[e]; }
;             *(u32x4*)gp = pack8(o);
	v_mul_f32_e32 v107, v107, v91
	v_mul_f32_e32 v108, v108, v92
	v_mul_f32_e32 v109, v109, v93
	v_mul_f32_e32 v110, v110, v94
	v_mul_f32_e32 v111, v111, v95
	v_fma_f32 v104, v104, v88, v88
	v_fma_f32 v105, v105, v89, v89
	v_fma_f32 v106, v106, v90, v90
	v_fma_f32 v107, v107, v91, v91
	v_fma_f32 v108, v108, v92, v92
	v_fma_f32 v109, v109, v93, v93
	v_fma_f32 v110, v110, v94, v94
	v_fma_f32 v111, v111, v95, v95
	v_mul_f32_e32 v104, 0x3fcc422a, v104
	v_mul_f32_e32 v105, 0x3fcc422a, v105
	v_mul_f32_e32 v106, 0x3fcc422a, v106
	v_mul_f32_e32 v107, 0x3fcc422a, v107
	v_mul_f32_e32 v108, 0x3fcc422a, v108
	v_mul_f32_e32 v109, 0x3fcc422a, v109
	v_mul_f32_e32 v110, 0x3fcc422a, v110
	v_mul_f32_e32 v111, 0x3fcc422a, v111
	v_mul_f32_e32 v104, 0xbfb8aa3b, v104
	v_mul_f32_e32 v105, 0xbfb8aa3b, v105
	v_mul_f32_e32 v106, 0xbfb8aa3b, v106
	v_mul_f32_e32 v107, 0xbfb8aa3b, v107
	v_mul_f32_e32 v108, 0xbfb8aa3b, v108
	v_mul_f32_e32 v109, 0xbfb8aa3b, v109
	v_mul_f32_e32 v110, 0xbfb8aa3b, v110
	v_mul_f32_e32 v111, 0xbfb8aa3b, v111
	v_exp_f32_e32 v104, v104
	v_exp_f32_e32 v105, v105
	v_exp_f32_e32 v106, v106
	v_exp_f32_e32 v107, v107
	v_exp_f32_e32 v108, v108
	v_exp_f32_e32 v109, v109
	v_exp_f32_e32 v110, v110
	v_exp_f32_e32 v111, v111
	v_add_f32_e32 v104, 1.0, v104
	v_add_f32_e32 v105, 1.0, v105
	v_add_f32_e32 v106, 1.0, v106
	v_add_f32_e32 v107, 1.0, v107
	v_add_f32_e32 v108, 1.0, v108
	v_add_f32_e32 v109, 1.0, v109
	v_add_f32_e32 v110, 1.0, v110
	v_add_f32_e32 v111, 1.0, v111
	v_rcp_f32_e32 v104, v104
	v_rcp_f32_e32 v105, v105
	v_rcp_f32_e32 v106, v106
	v_rcp_f32_e32 v107, v107
	v_rcp_f32_e32 v108, v108
	v_rcp_f32_e32 v109, v109
	v_rcp_f32_e32 v110, v110
	v_rcp_f32_e32 v111, v111
	v_mul_f32_e32 v104, v104, v88
	v_mul_f32_e32 v105, v105, v89
	v_mul_f32_e32 v106, v106, v90
	v_mul_f32_e32 v107, v107, v91
	v_mul_f32_e32 v108, v108, v92
	v_mul_f32_e32 v109, v109, v93
	v_mul_f32_e32 v110, v110, v94
	v_mul_f32_e32 v111, v111, v95
	v_mul_f32_e32 v104, v80, v104
	v_mul_f32_e32 v105, v81, v105
	v_mul_f32_e32 v106, v82, v106
	v_mul_f32_e32 v107, v83, v107
	v_mul_f32_e32 v108, v84, v108
	v_mul_f32_e32 v109, v85, v109
	v_mul_f32_e32 v110, v86, v110
	v_mul_f32_e32 v111, v87, v111
	v_cvt_pk_bf16_f32 v112, v104, v105
	v_cvt_pk_bf16_f32 v113, v106, v107
	v_cvt_pk_bf16_f32 v114, v108, v109
	v_cvt_pk_bf16_f32 v115, v110, v111
	global_store_dwordx4 v27, v[112:115], s[24:25]
	s_add_u32 s24, s24, 0x2800
	s_addc_u32 s25, s25, 0
	global_load_dwordx4 v[44:47], v26, s[12:13] nt
	global_load_dwordx4 v[48:51], v26, s[14:15] nt
	global_load_dwordx4 v[52:55], v26, s[96:97] nt
	s_add_u32 s12, s12, 0x800
	s_addc_u32 s13, s13, 0
	s_add_u32 s14, s14, 0x800
	s_addc_u32 s15, s15, 0
	s_add_u32 s96, s96, 0x2800
	s_addc_u32 s97, s97, 0
	s_waitcnt vmcnt(12)
	v_lshlrev_b32_e32 v80, 16, v56
	v_and_b32_e32 v81, 0xffff0000, v56
	v_lshlrev_b32_e32 v82, 16, v57
	v_and_b32_e32 v83, 0xffff0000, v57
	v_lshlrev_b32_e32 v84, 16, v58
	v_and_b32_e32 v85, 0xffff0000, v58
	v_lshlrev_b32_e32 v86, 16, v59
	v_and_b32_e32 v87, 0xffff0000, v59
	v_lshlrev_b32_e32 v96, 16, v60
	v_and_b32_e32 v97, 0xffff0000, v60
	v_lshlrev_b32_e32 v98, 16, v61
	v_and_b32_e32 v99, 0xffff0000, v61
	v_lshlrev_b32_e32 v100, 16, v62
	v_and_b32_e32 v101, 0xffff0000, v62
	v_lshlrev_b32_e32 v102, 16, v63
	v_and_b32_e32 v103, 0xffff0000, v63
	v_lshlrev_b32_e32 v88, 16, v64
	v_and_b32_e32 v89, 0xffff0000, v64
	v_lshlrev_b32_e32 v90, 16, v65
	v_and_b32_e32 v91, 0xffff0000, v65
	v_lshlrev_b32_e32 v92, 16, v66
	v_and_b32_e32 v93, 0xffff0000, v66
	v_lshlrev_b32_e32 v94, 16, v67
	v_and_b32_e32 v95, 0xffff0000, v67
	v_fmac_f32_e32 v80, v96, v18
	v_fmac_f32_e32 v81, v97, v19
	v_fmac_f32_e32 v82, v98, v20
	v_fmac_f32_e32 v83, v99, v21
	v_fmac_f32_e32 v84, v100, v22
	v_fmac_f32_e32 v85, v101, v23
	v_fmac_f32_e32 v86, v102, v24
	v_fmac_f32_e32 v87, v103, v25
	v_mul_f32_e32 v104, 0x3d372713, v88
	v_mul_f32_e32 v105, 0x3d372713, v89
	v_mul_f32_e32 v106, 0x3d372713, v90
	v_mul_f32_e32 v107, 0x3d372713, v91
	v_mul_f32_e32 v108, 0x3d372713, v92
	v_mul_f32_e32 v109, 0x3d372713, v93
	v_mul_f32_e32 v110, 0x3d372713, v94
	v_mul_f32_e32 v111, 0x3d372713, v95
	v_mul_f32_e32 v104, v104, v88
	v_mul_f32_e32 v105, v105, v89
	v_mul_f32_e32 v106, v106, v90
	v_mul_f32_e32 v107, v107, v91
	v_mul_f32_e32 v108, v108, v92
	v_mul_f32_e32 v109, v109, v93
	v_mul_f32_e32 v110, v110, v94
	v_mul_f32_e32 v111, v111, v95
	v_fma_f32 v104, v104, v88, v88
	v_fma_f32 v105, v105, v89, v89
	v_fma_f32 v106, v106, v90, v90
	v_fma_f32 v107, v107, v91, v91
	v_fma_f32 v108, v108, v92, v92
	v_fma_f32 v109, v109, v93, v93
	v_fma_f32 v110, v110, v94, v94
	v_fma_f32 v111, v111, v95, v95
	v_mul_f32_e32 v104, 0x3fcc422a, v104
	v_mul_f32_e32 v105, 0x3fcc422a, v105
	v_mul_f32_e32 v106, 0x3fcc422a, v106
	v_mul_f32_e32 v107, 0x3fcc422a, v107
	v_mul_f32_e32 v108, 0x3fcc422a, v108
	v_mul_f32_e32 v109, 0x3fcc422a, v109
	v_mul_f32_e32 v110, 0x3fcc422a, v110
	v_mul_f32_e32 v111, 0x3fcc422a, v111
	v_mul_f32_e32 v104, 0xbfb8aa3b, v104
	v_mul_f32_e32 v105, 0xbfb8aa3b, v105
	v_mul_f32_e32 v106, 0xbfb8aa3b, v106
	v_mul_f32_e32 v107, 0xbfb8aa3b, v107
	v_mul_f32_e32 v108, 0xbfb8aa3b, v108
	v_mul_f32_e32 v109, 0xbfb8aa3b, v109
	v_mul_f32_e32 v110, 0xbfb8aa3b, v110
	v_mul_f32_e32 v111, 0xbfb8aa3b, v111
	v_exp_f32_e32 v104, v104
	v_exp_f32_e32 v105, v105
	v_exp_f32_e32 v106, v106
	v_exp_f32_e32 v107, v107
	v_exp_f32_e32 v108, v108
	v_exp_f32_e32 v109, v109
	v_exp_f32_e32 v110, v110
	v_exp_f32_e32 v111, v111
	v_add_f32_e32 v104, 1.0, v104
	v_add_f32_e32 v105, 1.0, v105
	v_add_f32_e32 v106, 1.0, v106
	v_add_f32_e32 v107, 1.0, v107
	v_add_f32_e32 v108, 1.0, v108
	v_add_f32_e32 v109, 1.0, v109
	v_add_f32_e32 v110, 1.0, v110
	v_add_f32_e32 v111, 1.0, v111
	v_rcp_f32_e32 v104, v104
	v_rcp_f32_e32 v105, v105
	v_rcp_f32_e32 v106, v106
	v_rcp_f32_e32 v107, v107
	v_rcp_f32_e32 v108, v108
	v_rcp_f32_e32 v109, v109
	v_rcp_f32_e32 v110, v110
	v_rcp_f32_e32 v111, v111
	v_mul_f32_e32 v104, v104, v88
	v_mul_f32_e32 v105, v105, v89
	v_mul_f32_e32 v106, v106, v90
	v_mul_f32_e32 v107, v107, v91
	v_mul_f32_e32 v108, v108, v92
	v_mul_f32_e32 v109, v109, v93
	v_mul_f32_e32 v110, v110, v94
	v_mul_f32_e32 v111, v111, v95
	v_mul_f32_e32 v104, v80, v104
	v_mul_f32_e32 v105, v81, v105
	v_mul_f32_e32 v106, v82, v106
	v_mul_f32_e32 v107, v83, v107
	v_mul_f32_e32 v108, v84, v108
	v_mul_f32_e32 v109, v85, v109
	v_mul_f32_e32 v110, v86, v110
	v_mul_f32_e32 v111, v87, v111
	v_cvt_pk_bf16_f32 v112, v104, v105
	v_cvt_pk_bf16_f32 v113, v106, v107
	v_cvt_pk_bf16_f32 v114, v108, v109
	v_cvt_pk_bf16_f32 v115, v110, v111
	global_store_dwordx4 v27, v[112:115], s[24:25]
	s_add_u32 s24, s24, 0x2800
	s_addc_u32 s25, s25, 0
	global_load_dwordx4 v[56:59], v26, s[12:13] nt
	global_load_dwordx4 v[60:63], v26, s[14:15] nt
	global_load_dwordx4 v[64:67], v26, s[96:97] nt
	s_add_u32 s12, s12, 0x800
	s_addc_u32 s13, s13, 0
	s_add_u32 s14, s14, 0x800
	s_addc_u32 s15, s15, 0
	s_add_u32 s96, s96, 0x2800
	s_addc_u32 s97, s97, 0
	s_waitcnt vmcnt(12)
; __device__ __forceinline__ u32x4 pack8(const float (&f)[8]) { u32x4 o; o.x = cvt_pk_bf16(f[0], f[1]); o.y = cvt_pk_bf16(f[2], f[3]); o.z = cvt_pk_bf16(f[4], f[5]); o.w = cvt_pk_bf16(f[6], f[7]); return o; }
; __device__ __forceinline__ float gelu_tanh(float x) { return x * sigmoidf_(1.5957691216057308f * (x + 0.044715f * x * x * x)); }
; __device__ __forceinline__ void fixup_phase(KP p, int l) {
;     ...
;         for (int i = 0; i < 16; ++i) {
;             const size_t m = (size_t)(m0 + i);
;             float hl[8], pc[8], gr[8], o[8], h[8];
;             unpack8(__builtin_nontemporal_load((const u32x4*)(HLOC + m * D + c0)), hl); unpack8(__builtin_nontemporal_load((const u32x4*)(PCUM + m * D + c0)), pc);
;             bf16_t* gp = P + m * DP + C_GR + c0; unpack8(*(const u32x4*)gp, gr);
; #pragma unroll
;             for (int e = 0; e < 8; ++e) { h[e] = hl[e] + pc[e] * carry[e]; o[e] = gelu_tanh(gr[e]) * h[e]; }
;             *(u32x4*)gp = pack8(o);
	v_lshlrev_b32_e32 v80, 16, v68
	v_and_b32_e32 v81, 0xffff0000, v68
	v_lshlrev_b32_e32 v82, 16, v69
	v_and_b32_e32 v83, 0xffff0000, v69
	v_lshlrev_b32_e32 v84, 16, v70
	v_and_b32_e32 v85, 0xffff0000, v70
	v_lshlrev_b32_e32 v86, 16, v71
	v_and_b32_e32 v87, 0xffff0000, v71
	v_lshlrev_b32_e32 v96, 16, v72
	v_and_b32_e32 v97, 0xffff0000, v72
	v_lshlrev_b32_e32 v98, 16, v73
	v_and_b32_e32 v99, 0xffff0000, v73
	v_lshlrev_b32_e32 v100, 16, v74
	v_and_b32_e32 v101, 0xffff0000, v74
	v_lshlrev_b32_e32 v102, 16, v75
	v_and_b32_e32 v103, 0xffff0000, v75
	v_lshlrev_b32_e32 v88, 16, v76
	v_and_b32_e32 v89, 0xffff0000, v76
	v_lshlrev_b32_e32 v90, 16, v77
	v_and_b32_e32 v91, 0xffff0000, v77
	v_lshlrev_b32_e32 v92, 16, v78
	v_and_b32_e32 v93, 0xffff0000, v78
	v_lshlrev_b32_e32 v94, 16, v79
	v_and_b32_e32 v95, 0xffff0000, v79
	v_fmac_f32_e32 v80, v96, v18
	v_fmac_f32_e32 v81, v97, v19
	v_fmac_f32_e32 v82, v98, v20
	v_fmac_f32_e32 v83, v99, v21
	v_fmac_f32_e32 v84, v100, v22
	v_fmac_f32_e32 v85, v101, v23
	v_fmac_f32_e32 v86, v102, v24
	v_fmac_f32_e32 v87, v103, v25
	v_mul_f32_e32 v104, 0x3d372713, v88
	v_mul_f32_e32 v105, 0x3d372713, v89
	v_mul_f32_e32 v106, 0x3d372713, v90
	v_mul_f32_e32 v107, 0x3d372713, v91
	v_mul_f32_e32 v108, 0x3d372713, v92
	v_mul_f32_e32 v109, 0x3d372713, v93
	v_mul_f32_e32 v110, 0x3d372713, v94
	v_mul_f32_e32 v111, 0x3d372713, v95
	v_mul_f32_e32 v104, v104, v88
	v_mul_f32_e32 v105, v105, v89
	v_mul_f32_e32 v106, v106, v90
	v_mul_f32_e32 v107, v107, v91
	v_mul_f32_e32 v108, v108, v92
	v_mul_f32_e32 v109, v109, v93
	v_mul_f32_e32 v110, v110, v94
	v_mul_f32_e32 v111, v111, v95
	v_fma_f32 v104, v104, v88, v88
	v_fma_f32 v105, v105, v89, v89
	v_fma_f32 v106, v106, v90, v90
	v_fma_f32 v107, v107, v91, v91
	v_fma_f32 v108, v108, v92, v92
	v_fma_f32 v109, v109, v93, v93
	v_fma_f32 v110, v110, v94, v94
	v_fma_f32 v111, v111, v95, v95
	v_mul_f32_e32 v104, 0x3fcc422a, v104
	v_mul_f32_e32 v105, 0x3fcc422a, v105
	v_mul_f32_e32 v106, 0x3fcc422a, v106
	v_mul_f32_e32 v107, 0x3fcc422a, v107
	v_mul_f32_e32 v108, 0x3fcc422a, v108
	v_mul_f32_e32 v109, 0x3fcc422a, v109
	v_mul_f32_e32 v110, 0x3fcc422a, v110
	v_mul_f32_e32 v111, 0x3fcc422a, v111
	v_mul_f32_e32 v104, 0xbfb8aa3b, v104
	v_mul_f32_e32 v105, 0xbfb8aa3b, v105
	v_mul_f32_e32 v106, 0xbfb8aa3b, v106
	v_mul_f32_e32 v107, 0xbfb8aa3b, v107
	v_mul_f32_e32 v108, 0xbfb8aa3b, v108
	v_mul_f32_e32 v109, 0xbfb8aa3b, v109
	v_mul_f32_e32 v110, 0xbfb8aa3b, v110
	v_mul_f32_e32 v111, 0xbfb8aa3b, v111
	v_exp_f32_e32 v104, v104
	v_exp_f32_e32 v105, v105
	v_exp_f32_e32 v106, v106
	v_exp_f32_e32 v107, v107
	v_exp_f32_e32 v108, v108
	v_exp_f32_e32 v109, v109
	v_exp_f32_e32 v110, v110
	v_exp_f32_e32 v111, v111
	v_add_f32_e32 v104, 1.0, v104
	v_add_f32_e32 v105, 1.0, v105
	v_add_f32_e32 v106, 1.0, v106
	v_add_f32_e32 v107, 1.0, v107
	v_add_f32_e32 v108, 1.0, v108
	v_add_f32_e32 v109, 1.0, v109
	v_add_f32_e32 v110, 1.0, v110
	v_add_f32_e32 v111, 1.0, v111
	v_rcp_f32_e32 v104, v104
	v_rcp_f32_e32 v105, v105
	v_rcp_f32_e32 v106, v106
	v_rcp_f32_e32 v107, v107
	v_rcp_f32_e32 v108, v108
	v_rcp_f32_e32 v109, v109
	v_rcp_f32_e32 v110, v110
	v_rcp_f32_e32 v111, v111
	v_mul_f32_e32 v104, v104, v88
	v_mul_f32_e32 v105, v105, v89
	v_mul_f32_e32 v106, v106, v90
	v_mul_f32_e32 v107, v107, v91
	v_mul_f32_e32 v108, v108, v92
	v_mul_f32_e32 v109, v109, v93
	v_mul_f32_e32 v110, v110, v94
	v_mul_f32_e32 v111, v111, v95
	v_mul_f32_e32 v104, v80, v104
	v_mul_f32_e32 v105, v81, v105
	v_mul_f32_e32 v106, v82, v106
	v_mul_f32_e32 v107, v83, v107
	v_mul_f32_e32 v108, v84, v108
	v_mul_f32_e32 v109, v85, v109
	v_mul_f32_e32 v110, v86, v110
	v_mul_f32_e32 v111, v87, v111
	v_cvt_pk_bf16_f32 v112, v104, v105
	v_cvt_pk_bf16_f32 v113, v106, v107
	v_cvt_pk_bf16_f32 v114, v108, v109
	v_cvt_pk_bf16_f32 v115, v110, v111
	global_store_dwordx4 v27, v[112:115], s[24:25]
	s_add_u32 s24, s24, 0x2800
	s_addc_u32 s25, s25, 0
	global_load_dwordx4 v[68:71], v26, s[12:13] nt
	global_load_dwordx4 v[72:75], v26, s[14:15] nt
	global_load_dwordx4 v[76:79], v26, s[96:97] nt
	s_add_u32 s12, s12, 0x800
	s_addc_u32 s13, s13, 0
	s_add_u32 s14, s14, 0x800
	s_addc_u32 s15, s15, 0
	s_add_u32 s96, s96, 0x2800
	s_addc_u32 s97, s97, 0
	s_waitcnt vmcnt(12)
	v_lshlrev_b32_e32 v80, 16, v32
	v_and_b32_e32 v81, 0xffff0000, v32
	v_lshlrev_b32_e32 v82, 16, v33
	v_and_b32_e32 v83, 0xffff0000, v33
	v_lshlrev_b32_e32 v84, 16, v34
	v_and_b32_e32 v85, 0xffff0000, v34
	v_lshlrev_b32_e32 v86, 16, v35
	v_and_b32_e32 v87, 0xffff0000, v35
	v_lshlrev_b32_e32 v96, 16, v36
	v_and_b32_e32 v97, 0xffff0000, v36
	v_lshlrev_b32_e32 v98, 16, v37
	v_and_b32_e32 v99, 0xffff0000, v37
	v_lshlrev_b32_e32 v100, 16, v38
	v_and_b32_e32 v101, 0xffff0000, v38
	v_lshlrev_b32_e32 v102, 16, v39
	v_and_b32_e32 v103, 0xffff0000, v39
	v_lshlrev_b32_e32 v88, 16, v40
	v_and_b32_e32 v89, 0xffff0000, v40
	v_lshlrev_b32_e32 v90, 16, v41
	v_and_b32_e32 v91, 0xffff0000, v41
	v_lshlrev_b32_e32 v92, 16, v42
	v_and_b32_e32 v93, 0xffff0000, v42
	v_lshlrev_b32_e32 v94, 16, v43
	v_and_b32_e32 v95, 0xffff0000, v43
	v_fmac_f32_e32 v80, v96, v18
	v_fmac_f32_e32 v81, v97, v19
	v_fmac_f32_e32 v82, v98, v20
	v_fmac_f32_e32 v83, v99, v21
	v_fmac_f32_e32 v84, v100, v22
	v_fmac_f32_e32 v85, v101, v23
	v_fmac_f32_e32 v86, v102, v24
	v_fmac_f32_e32 v87, v103, v25
	v_mul_f32_e32 v104, 0x3d372713, v88
	v_mul_f32_e32 v105, 0x3d372713, v89
	v_mul_f32_e32 v106, 0x3d372713, v90
	v_mul_f32_e32 v107, 0x3d372713, v91
	v_mul_f32_e32 v108, 0x3d372713, v92
	v_mul_f32_e32 v109, 0x3d372713, v93
	v_mul_f32_e32 v110, 0x3d372713, v94
	v_mul_f32_e32 v111, 0x3d372713, v95
	v_mul_f32_e32 v104, v104, v88
	v_mul_f32_e32 v105, v105, v89
	v_mul_f32_e32 v106, v106, v90
; __device__ __forceinline__ u32x4 pack8(const float (&f)[8]) { u32x4 o; o.x = cvt_pk_bf16(f[0], f[1]); o.y = cvt_pk_bf16(f[2], f[3]); o.z = cvt_pk_bf16(f[4], f[5]); o.w = cvt_pk_bf16(f[6], f[7]); return o; }
; __device__ __forceinline__ float gelu_tanh(float x) { return x * sigmoidf_(1.5957691216057308f * (x + 0.044715f * x * x * x)); }
; __device__ __forceinline__ void fixup_phase(KP p, int l) {
;     ...
;         for (int i = 0; i < 16; ++i) {
;             const size_t m = (size_t)(m0 + i);
;             float hl[8], pc[8], gr[8], o[8], h[8];
;             unpack8(__builtin_nontemporal_load((const u32x4*)(HLOC + m * D + c0)), hl); unpack8(__builtin_nontemporal_load((const u32x4*)(PCUM + m * D + c0)), pc);
;             bf16_t* gp = P + m * DP + C_GR + c0; unpack8(*(const u32x4*)gp, gr);
; #pragma unroll
;             for (int e = 0; e < 8; ++e) { h[e] = hl[e] + pc[e] * carry[e]; o[e] = gelu_tanh(gr[e]) * h[e]; }
;             *(u32x4*)gp = pack8(o);
	v_mul_f32_e32 v107, v107, v91
	v_mul_f32_e32 v108, v108, v92
	v_mul_f32_e32 v109, v109, v93
	v_mul_f32_e32 v110, v110, v94
	v_mul_f32_e32 v111, v111, v95
	v_fma_f32 v104, v104, v88, v88
	v_fma_f32 v105, v105, v89, v89
	v_fma_f32 v106, v106, v90, v90
	v_fma_f32 v107, v107, v91, v91
	v_fma_f32 v108, v108, v92, v92
	v_fma_f32 v109, v109, v93, v93
	v_fma_f32 v110, v110, v94, v94
	v_fma_f32 v111, v111, v95, v95
	v_mul_f32_e32 v104, 0x3fcc422a, v104
	v_mul_f32_e32 v105, 0x3fcc422a, v105
	v_mul_f32_e32 v106, 0x3fcc422a, v106
	v_mul_f32_e32 v107, 0x3fcc422a, v107
	v_mul_f32_e32 v108, 0x3fcc422a, v108
	v_mul_f32_e32 v109, 0x3fcc422a, v109
	v_mul_f32_e32 v110, 0x3fcc422a, v110
	v_mul_f32_e32 v111, 0x3fcc422a, v111
	v_mul_f32_e32 v104, 0xbfb8aa3b, v104
	v_mul_f32_e32 v105, 0xbfb8aa3b, v105
	v_mul_f32_e32 v106, 0xbfb8aa3b, v106
	v_mul_f32_e32 v107, 0xbfb8aa3b, v107
	v_mul_f32_e32 v108, 0xbfb8aa3b, v108
	v_mul_f32_e32 v109, 0xbfb8aa3b, v109
	v_mul_f32_e32 v110, 0xbfb8aa3b, v110
	v_mul_f32_e32 v111, 0xbfb8aa3b, v111
	v_exp_f32_e32 v104, v104
	v_exp_f32_e32 v105, v105
	v_exp_f32_e32 v106, v106
	v_exp_f32_e32 v107, v107
	v_exp_f32_e32 v108, v108
	v_exp_f32_e32 v109, v109
	v_exp_f32_e32 v110, v110
	v_exp_f32_e32 v111, v111
	v_add_f32_e32 v104, 1.0, v104
	v_add_f32_e32 v105, 1.0, v105
	v_add_f32_e32 v106, 1.0, v106
	v_add_f32_e32 v107, 1.0, v107
	v_add_f32_e32 v108, 1.0, v108
	v_add_f32_e32 v109, 1.0, v109
	v_add_f32_e32 v110, 1.0, v110
	v_add_f32_e32 v111, 1.0, v111
	v_rcp_f32_e32 v104, v104
	v_rcp_f32_e32 v105, v105
	v_rcp_f32_e32 v106, v106
	v_rcp_f32_e32 v107, v107
	v_rcp_f32_e32 v108, v108
	v_rcp_f32_e32 v109, v109
	v_rcp_f32_e32 v110, v110
	v_rcp_f32_e32 v111, v111
	v_mul_f32_e32 v104, v104, v88
	v_mul_f32_e32 v105, v105, v89
	v_mul_f32_e32 v106, v106, v90
	v_mul_f32_e32 v107, v107, v91
	v_mul_f32_e32 v108, v108, v92
	v_mul_f32_e32 v109, v109, v93
	v_mul_f32_e32 v110, v110, v94
	v_mul_f32_e32 v111, v111, v95
	v_mul_f32_e32 v104, v80, v104
	v_mul_f32_e32 v105, v81, v105
	v_mul_f32_e32 v106, v82, v106
	v_mul_f32_e32 v107, v83, v107
	v_mul_f32_e32 v108, v84, v108
	v_mul_f32_e32 v109, v85, v109
	v_mul_f32_e32 v110, v86, v110
	v_mul_f32_e32 v111, v87, v111
	v_cvt_pk_bf16_f32 v112, v104, v105
	v_cvt_pk_bf16_f32 v113, v106, v107
	v_cvt_pk_bf16_f32 v114, v108, v109
	v_cvt_pk_bf16_f32 v115, v110, v111
	global_store_dwordx4 v27, v[112:115], s[24:25]
	s_add_u32 s24, s24, 0x2800
	s_addc_u32 s25, s25, 0
	global_load_dwordx4 v[32:35], v26, s[12:13] nt
	global_load_dwordx4 v[36:39], v26, s[14:15] nt
	global_load_dwordx4 v[40:43], v26, s[96:97] nt
	s_add_u32 s12, s12, 0x800
	s_addc_u32 s13, s13, 0
	s_add_u32 s14, s14, 0x800
	s_addc_u32 s15, s15, 0
	s_add_u32 s96, s96, 0x2800
	s_addc_u32 s97, s97, 0
	s_waitcnt vmcnt(12)
	v_lshlrev_b32_e32 v80, 16, v44
	v_and_b32_e32 v81, 0xffff0000, v44
	v_lshlrev_b32_e32 v82, 16, v45
	v_and_b32_e32 v83, 0xffff0000, v45
	v_lshlrev_b32_e32 v84, 16, v46
	v_and_b32_e32 v85, 0xffff0000, v46
	v_lshlrev_b32_e32 v86, 16, v47
	v_and_b32_e32 v87, 0xffff0000, v47
	v_lshlrev_b32_e32 v96, 16, v48
	v_and_b32_e32 v97, 0xffff0000, v48
	v_lshlrev_b32_e32 v98, 16, v49
	v_and_b32_e32 v99, 0xffff0000, v49
	v_lshlrev_b32_e32 v100, 16, v50
	v_and_b32_e32 v101, 0xffff0000, v50
	v_lshlrev_b32_e32 v102, 16, v51
	v_and_b32_e32 v103, 0xffff0000, v51
	v_lshlrev_b32_e32 v88, 16, v52
	v_and_b32_e32 v89, 0xffff0000, v52
	v_lshlrev_b32_e32 v90, 16, v53
	v_and_b32_e32 v91, 0xffff0000, v53
	v_lshlrev_b32_e32 v92, 16, v54
	v_and_b32_e32 v93, 0xffff0000, v54
	v_lshlrev_b32_e32 v94, 16, v55
	v_and_b32_e32 v95, 0xffff0000, v55
	v_fmac_f32_e32 v80, v96, v18
	v_fmac_f32_e32 v81, v97, v19
	v_fmac_f32_e32 v82, v98, v20
	v_fmac_f32_e32 v83, v99, v21
	v_fmac_f32_e32 v84, v100, v22
	v_fmac_f32_e32 v85, v101, v23
	v_fmac_f32_e32 v86, v102, v24
	v_fmac_f32_e32 v87, v103, v25
	v_mul_f32_e32 v104, 0x3d372713, v88
	v_mul_f32_e32 v105, 0x3d372713, v89
	v_mul_f32_e32 v106, 0x3d372713, v90
	v_mul_f32_e32 v107, 0x3d372713, v91
	v_mul_f32_e32 v108, 0x3d372713, v92
	v_mul_f32_e32 v109, 0x3d372713, v93
	v_mul_f32_e32 v110, 0x3d372713, v94
	v_mul_f32_e32 v111, 0x3d372713, v95
	v_mul_f32_e32 v104, v104, v88
	v_mul_f32_e32 v105, v105, v89
	v_mul_f32_e32 v106, v106, v90
	v_mul_f32_e32 v107, v107, v91
	v_mul_f32_e32 v108, v108, v92
	v_mul_f32_e32 v109, v109, v93
	v_mul_f32_e32 v110, v110, v94
	v_mul_f32_e32 v111, v111, v95
	v_fma_f32 v104, v104, v88, v88
	v_fma_f32 v105, v105, v89, v89
	v_fma_f32 v106, v106, v90, v90
	v_fma_f32 v107, v107, v91, v91
	v_fma_f32 v108, v108, v92, v92
	v_fma_f32 v109, v109, v93, v93
	v_fma_f32 v110, v110, v94, v94
	v_fma_f32 v111, v111, v95, v95
	v_mul_f32_e32 v104, 0x3fcc422a, v104
	v_mul_f32_e32 v105, 0x3fcc422a, v105
	v_mul_f32_e32 v106, 0x3fcc422a, v106
	v_mul_f32_e32 v107, 0x3fcc422a, v107
	v_mul_f32_e32 v108, 0x3fcc422a, v108
	v_mul_f32_e32 v109, 0x3fcc422a, v109
	v_mul_f32_e32 v110, 0x3fcc422a, v110
	v_mul_f32_e32 v111, 0x3fcc422a, v111
	v_mul_f32_e32 v104, 0xbfb8aa3b, v104
	v_mul_f32_e32 v105, 0xbfb8aa3b, v105
	v_mul_f32_e32 v106, 0xbfb8aa3b, v106
	v_mul_f32_e32 v107, 0xbfb8aa3b, v107
	v_mul_f32_e32 v108, 0xbfb8aa3b, v108
	v_mul_f32_e32 v109, 0xbfb8aa3b, v109
	v_mul_f32_e32 v110, 0xbfb8aa3b, v110
	v_mul_f32_e32 v111, 0xbfb8aa3b, v111
	v_exp_f32_e32 v104, v104
	v_exp_f32_e32 v105, v105
	v_exp_f32_e32 v106, v106
	v_exp_f32_e32 v107, v107
	v_exp_f32_e32 v108, v108
	v_exp_f32_e32 v109, v109
	v_exp_f32_e32 v110, v110
	v_exp_f32_e32 v111, v111
	v_add_f32_e32 v104, 1.0, v104
	v_add_f32_e32 v105, 1.0, v105
	v_add_f32_e32 v106, 1.0, v106
	v_add_f32_e32 v107, 1.0, v107
	v_add_f32_e32 v108, 1.0, v108
	v_add_f32_e32 v109, 1.0, v109
	v_add_f32_e32 v110, 1.0, v110
	v_add_f32_e32 v111, 1.0, v111
	v_rcp_f32_e32 v104, v104
	v_rcp_f32_e32 v105, v105
	v_rcp_f32_e32 v106, v106
	v_rcp_f32_e32 v107, v107
	v_rcp_f32_e32 v108, v108
	v_rcp_f32_e32 v109, v109
	v_rcp_f32_e32 v110, v110
	v_rcp_f32_e32 v111, v111
	v_mul_f32_e32 v104, v104, v88
	v_mul_f32_e32 v105, v105, v89
	v_mul_f32_e32 v106, v106, v90
	v_mul_f32_e32 v107, v107, v91
	v_mul_f32_e32 v108, v108, v92
	v_mul_f32_e32 v109, v109, v93
	v_mul_f32_e32 v110, v110, v94
	v_mul_f32_e32 v111, v111, v95
	v_mul_f32_e32 v104, v80, v104
	v_mul_f32_e32 v105, v81, v105
	v_mul_f32_e32 v106, v82, v106
	v_mul_f32_e32 v107, v83, v107
	v_mul_f32_e32 v108, v84, v108
	v_mul_f32_e32 v109, v85, v109
	v_mul_f32_e32 v110, v86, v110
	v_mul_f32_e32 v111, v87, v111
	v_cvt_pk_bf16_f32 v112, v104, v105
	v_cvt_pk_bf16_f32 v113, v106, v107
	v_cvt_pk_bf16_f32 v114, v108, v109
	v_cvt_pk_bf16_f32 v115, v110, v111
	global_store_dwordx4 v27, v[112:115], s[24:25]
	s_add_u32 s24, s24, 0x2800
	s_addc_u32 s25, s25, 0
	global_load_dwordx4 v[44:47], v26, s[12:13] nt
	global_load_dwordx4 v[48:51], v26, s[14:15] nt
	global_load_dwordx4 v[52:55], v26, s[96:97] nt
	s_add_u32 s12, s12, 0x800
	s_addc_u32 s13, s13, 0
	s_add_u32 s14, s14, 0x800
	s_addc_u32 s15, s15, 0
	s_add_u32 s96, s96, 0x2800
	s_addc_u32 s97, s97, 0
	s_waitcnt vmcnt(12)
; __device__ __forceinline__ u32x4 pack8(const float (&f)[8]) { u32x4 o; o.x = cvt_pk_bf16(f[0], f[1]); o.y = cvt_pk_bf16(f[2], f[3]); o.z = cvt_pk_bf16(f[4], f[5]); o.w = cvt_pk_bf16(f[6], f[7]); return o; }
; __device__ __forceinline__ float gelu_tanh(float x) { return x * sigmoidf_(1.5957691216057308f * (x + 0.044715f * x * x * x)); }
; __device__ __forceinline__ void fixup_phase(KP p, int l) {
;     ...
;         for (int i = 0; i < 16; ++i) {
;             const size_t m = (size_t)(m0 + i);
;             float hl[8], pc[8], gr[8], o[8], h[8];
;             unpack8(__builtin_nontemporal_load((const u32x4*)(HLOC + m * D + c0)), hl); unpack8(__builtin_nontemporal_load((const u32x4*)(PCUM + m * D + c0)), pc);
;             bf16_t* gp = P + m * DP + C_GR + c0; unpack8(*(const u32x4*)gp, gr);
; #pragma unroll
;             for (int e = 0; e < 8; ++e) { h[e] = hl[e] + pc[e] * carry[e]; o[e] = gelu_tanh(gr[e]) * h[e]; }
;             *(u32x4*)gp = pack8(o);
	v_lshlrev_b32_e32 v80, 16, v56
	v_and_b32_e32 v81, 0xffff0000, v56
	v_lshlrev_b32_e32 v82, 16, v57
	v_and_b32_e32 v83, 0xffff0000, v57
	v_lshlrev_b32_e32 v84, 16, v58
	v_and_b32_e32 v85, 0xffff0000, v58
	v_lshlrev_b32_e32 v86, 16, v59
	v_and_b32_e32 v87, 0xffff0000, v59
	v_lshlrev_b32_e32 v96, 16, v60
	v_and_b32_e32 v97, 0xffff0000, v60
	v_lshlrev_b32_e32 v98, 16, v61
	v_and_b32_e32 v99, 0xffff0000, v61
	v_lshlrev_b32_e32 v100, 16, v62
	v_and_b32_e32 v101, 0xffff0000, v62
	v_lshlrev_b32_e32 v102, 16, v63
	v_and_b32_e32 v103, 0xffff0000, v63
	v_lshlrev_b32_e32 v88, 16, v64
	v_and_b32_e32 v89, 0xffff0000, v64
	v_lshlrev_b32_e32 v90, 16, v65
	v_and_b32_e32 v91, 0xffff0000, v65
	v_lshlrev_b32_e32 v92, 16, v66
	v_and_b32_e32 v93, 0xffff0000, v66
	v_lshlrev_b32_e32 v94, 16, v67
	v_and_b32_e32 v95, 0xffff0000, v67
	v_fmac_f32_e32 v80, v96, v18
	v_fmac_f32_e32 v81, v97, v19
	v_fmac_f32_e32 v82, v98, v20
	v_fmac_f32_e32 v83, v99, v21
	v_fmac_f32_e32 v84, v100, v22
	v_fmac_f32_e32 v85, v101, v23
	v_fmac_f32_e32 v86, v102, v24
	v_fmac_f32_e32 v87, v103, v25
	v_mul_f32_e32 v104, 0x3d372713, v88
	v_mul_f32_e32 v105, 0x3d372713, v89
	v_mul_f32_e32 v106, 0x3d372713, v90
	v_mul_f32_e32 v107, 0x3d372713, v91
	v_mul_f32_e32 v108, 0x3d372713, v92
	v_mul_f32_e32 v109, 0x3d372713, v93
	v_mul_f32_e32 v110, 0x3d372713, v94
	v_mul_f32_e32 v111, 0x3d372713, v95
	v_mul_f32_e32 v104, v104, v88
	v_mul_f32_e32 v105, v105, v89
	v_mul_f32_e32 v106, v106, v90
	v_mul_f32_e32 v107, v107, v91
	v_mul_f32_e32 v108, v108, v92
	v_mul_f32_e32 v109, v109, v93
	v_mul_f32_e32 v110, v110, v94
	v_mul_f32_e32 v111, v111, v95
	v_fma_f32 v104, v104, v88, v88
	v_fma_f32 v105, v105, v89, v89
	v_fma_f32 v106, v106, v90, v90
	v_fma_f32 v107, v107, v91, v91
	v_fma_f32 v108, v108, v92, v92
	v_fma_f32 v109, v109, v93, v93
	v_fma_f32 v110, v110, v94, v94
	v_fma_f32 v111, v111, v95, v95
	v_mul_f32_e32 v104, 0x3fcc422a, v104
	v_mul_f32_e32 v105, 0x3fcc422a, v105
	v_mul_f32_e32 v106, 0x3fcc422a, v106
	v_mul_f32_e32 v107, 0x3fcc422a, v107
	v_mul_f32_e32 v108, 0x3fcc422a, v108
	v_mul_f32_e32 v109, 0x3fcc422a, v109
	v_mul_f32_e32 v110, 0x3fcc422a, v110
	v_mul_f32_e32 v111, 0x3fcc422a, v111
	v_mul_f32_e32 v104, 0xbfb8aa3b, v104
	v_mul_f32_e32 v105, 0xbfb8aa3b, v105
	v_mul_f32_e32 v106, 0xbfb8aa3b, v106
	v_mul_f32_e32 v107, 0xbfb8aa3b, v107
	v_mul_f32_e32 v108, 0xbfb8aa3b, v108
	v_mul_f32_e32 v109, 0xbfb8aa3b, v109
	v_mul_f32_e32 v110, 0xbfb8aa3b, v110
	v_mul_f32_e32 v111, 0xbfb8aa3b, v111
	v_exp_f32_e32 v104, v104
	v_exp_f32_e32 v105, v105
	v_exp_f32_e32 v106, v106
	v_exp_f32_e32 v107, v107
	v_exp_f32_e32 v108, v108
	v_exp_f32_e32 v109, v109
	v_exp_f32_e32 v110, v110
	v_exp_f32_e32 v111, v111
	v_add_f32_e32 v104, 1.0, v104
	v_add_f32_e32 v105, 1.0, v105
	v_add_f32_e32 v106, 1.0, v106
	v_add_f32_e32 v107, 1.0, v107
	v_add_f32_e32 v108, 1.0, v108
	v_add_f32_e32 v109, 1.0, v109
	v_add_f32_e32 v110, 1.0, v110
	v_add_f32_e32 v111, 1.0, v111
	v_rcp_f32_e32 v104, v104
	v_rcp_f32_e32 v105, v105
	v_rcp_f32_e32 v106, v106
	v_rcp_f32_e32 v107, v107
	v_rcp_f32_e32 v108, v108
	v_rcp_f32_e32 v109, v109
	v_rcp_f32_e32 v110, v110
	v_rcp_f32_e32 v111, v111
	v_mul_f32_e32 v104, v104, v88
	v_mul_f32_e32 v105, v105, v89
	v_mul_f32_e32 v106, v106, v90
	v_mul_f32_e32 v107, v107, v91
	v_mul_f32_e32 v108, v108, v92
	v_mul_f32_e32 v109, v109, v93
	v_mul_f32_e32 v110, v110, v94
	v_mul_f32_e32 v111, v111, v95
	v_mul_f32_e32 v104, v80, v104
	v_mul_f32_e32 v105, v81, v105
	v_mul_f32_e32 v106, v82, v106
	v_mul_f32_e32 v107, v83, v107
	v_mul_f32_e32 v108, v84, v108
	v_mul_f32_e32 v109, v85, v109
	v_mul_f32_e32 v110, v86, v110
	v_mul_f32_e32 v111, v87, v111
	v_cvt_pk_bf16_f32 v112, v104, v105
	v_cvt_pk_bf16_f32 v113, v106, v107
	v_cvt_pk_bf16_f32 v114, v108, v109
	v_cvt_pk_bf16_f32 v115, v110, v111
	global_store_dwordx4 v27, v[112:115], s[24:25]
	s_add_u32 s24, s24, 0x2800
	s_addc_u32 s25, s25, 0
	global_load_dwordx4 v[56:59], v26, s[12:13] nt
	global_load_dwordx4 v[60:63], v26, s[14:15] nt
	global_load_dwordx4 v[64:67], v26, s[96:97] nt
	s_add_u32 s12, s12, 0x800
	s_addc_u32 s13, s13, 0
	s_add_u32 s14, s14, 0x800
	s_addc_u32 s15, s15, 0
	s_add_u32 s96, s96, 0x2800
	s_addc_u32 s97, s97, 0
	s_waitcnt vmcnt(12)
	v_lshlrev_b32_e32 v80, 16, v68
	v_and_b32_e32 v81, 0xffff0000, v68
	v_lshlrev_b32_e32 v82, 16, v69
	v_and_b32_e32 v83, 0xffff0000, v69
	v_lshlrev_b32_e32 v84, 16, v70
	v_and_b32_e32 v85, 0xffff0000, v70
	v_lshlrev_b32_e32 v86, 16, v71
	v_and_b32_e32 v87, 0xffff0000, v71
	v_lshlrev_b32_e32 v96, 16, v72
	v_and_b32_e32 v97, 0xffff0000, v72
	v_lshlrev_b32_e32 v98, 16, v73
	v_and_b32_e32 v99, 0xffff0000, v73
	v_lshlrev_b32_e32 v100, 16, v74
	v_and_b32_e32 v101, 0xffff0000, v74
	v_lshlrev_b32_e32 v102, 16, v75
	v_and_b32_e32 v103, 0xffff0000, v75
	v_lshlrev_b32_e32 v88, 16, v76
	v_and_b32_e32 v89, 0xffff0000, v76
	v_lshlrev_b32_e32 v90, 16, v77
	v_and_b32_e32 v91, 0xffff0000, v77
	v_lshlrev_b32_e32 v92, 16, v78
	v_and_b32_e32 v93, 0xffff0000, v78
	v_lshlrev_b32_e32 v94, 16, v79
	v_and_b32_e32 v95, 0xffff0000, v79
	v_fmac_f32_e32 v80, v96, v18
	v_fmac_f32_e32 v81, v97, v19
	v_fmac_f32_e32 v82, v98, v20
	v_fmac_f32_e32 v83, v99, v21
	v_fmac_f32_e32 v84, v100, v22
	v_fmac_f32_e32 v85, v101, v23
	v_fmac_f32_e32 v86, v102, v24
	v_fmac_f32_e32 v87, v103, v25
	v_mul_f32_e32 v104, 0x3d372713, v88
	v_mul_f32_e32 v105, 0x3d372713, v89
	v_mul_f32_e32 v106, 0x3d372713, v90
	v_mul_f32_e32 v107, 0x3d372713, v91
	v_mul_f32_e32 v108, 0x3d372713, v92
	v_mul_f32_e32 v109, 0x3d372713, v93
	v_mul_f32_e32 v110, 0x3d372713, v94
	v_mul_f32_e32 v111, 0x3d372713, v95
	v_mul_f32_e32 v104, v104, v88
	v_mul_f32_e32 v105, v105, v89
	v_mul_f32_e32 v106, v106, v90
; __device__ __forceinline__ u32x4 pack8(const float (&f)[8]) { u32x4 o; o.x = cvt_pk_bf16(f[0], f[1]); o.y = cvt_pk_bf16(f[2], f[3]); o.z = cvt_pk_bf16(f[4], f[5]); o.w = cvt_pk_bf16(f[6], f[7]); return o; }
; __device__ __forceinline__ float gelu_tanh(float x) { return x * sigmoidf_(1.5957691216057308f * (x + 0.044715f * x * x * x)); }
; __device__ __forceinline__ void fixup_phase(KP p, int l) {
;     ...
;         for (int i = 0; i < 16; ++i) {
;             const size_t m = (size_t)(m0 + i);
;             float hl[8], pc[8], gr[8], o[8], h[8];
;             unpack8(__builtin_nontemporal_load((const u32x4*)(HLOC + m * D + c0)), hl); unpack8(__builtin_nontemporal_load((const u32x4*)(PCUM + m * D + c0)), pc);
;             bf16_t* gp = P + m * DP + C_GR + c0; unpack8(*(const u32x4*)gp, gr);
; #pragma unroll
;             for (int e = 0; e < 8; ++e) { h[e] = hl[e] + pc[e] * carry[e]; o[e] = gelu_tanh(gr[e]) * h[e]; }
;             *(u32x4*)gp = pack8(o);
	v_mul_f32_e32 v107, v107, v91
	v_mul_f32_e32 v108, v108, v92
	v_mul_f32_e32 v109, v109, v93
	v_mul_f32_e32 v110, v110, v94
	v_mul_f32_e32 v111, v111, v95
	v_fma_f32 v104, v104, v88, v88
	v_fma_f32 v105, v105, v89, v89
	v_fma_f32 v106, v106, v90, v90
	v_fma_f32 v107, v107, v91, v91
	v_fma_f32 v108, v108, v92, v92
	v_fma_f32 v109, v109, v93, v93
	v_fma_f32 v110, v110, v94, v94
	v_fma_f32 v111, v111, v95, v95
	v_mul_f32_e32 v104, 0x3fcc422a, v104
	v_mul_f32_e32 v105, 0x3fcc422a, v105
	v_mul_f32_e32 v106, 0x3fcc422a, v106
	v_mul_f32_e32 v107, 0x3fcc422a, v107
	v_mul_f32_e32 v108, 0x3fcc422a, v108
	v_mul_f32_e32 v109, 0x3fcc422a, v109
	v_mul_f32_e32 v110, 0x3fcc422a, v110
	v_mul_f32_e32 v111, 0x3fcc422a, v111
	v_mul_f32_e32 v104, 0xbfb8aa3b, v104
	v_mul_f32_e32 v105, 0xbfb8aa3b, v105
	v_mul_f32_e32 v106, 0xbfb8aa3b, v106
	v_mul_f32_e32 v107, 0xbfb8aa3b, v107
	v_mul_f32_e32 v108, 0xbfb8aa3b, v108
	v_mul_f32_e32 v109, 0xbfb8aa3b, v109
	v_mul_f32_e32 v110, 0xbfb8aa3b, v110
	v_mul_f32_e32 v111, 0xbfb8aa3b, v111
	v_exp_f32_e32 v104, v104
	v_exp_f32_e32 v105, v105
	v_exp_f32_e32 v106, v106
	v_exp_f32_e32 v107, v107
	v_exp_f32_e32 v108, v108
	v_exp_f32_e32 v109, v109
	v_exp_f32_e32 v110, v110
	v_exp_f32_e32 v111, v111
	v_add_f32_e32 v104, 1.0, v104
	v_add_f32_e32 v105, 1.0, v105
	v_add_f32_e32 v106, 1.0, v106
	v_add_f32_e32 v107, 1.0, v107
	v_add_f32_e32 v108, 1.0, v108
	v_add_f32_e32 v109, 1.0, v109
	v_add_f32_e32 v110, 1.0, v110
	v_add_f32_e32 v111, 1.0, v111
	v_rcp_f32_e32 v104, v104
	v_rcp_f32_e32 v105, v105
	v_rcp_f32_e32 v106, v106
	v_rcp_f32_e32 v107, v107
	v_rcp_f32_e32 v108, v108
	v_rcp_f32_e32 v109, v109
	v_rcp_f32_e32 v110, v110
	v_rcp_f32_e32 v111, v111
	v_mul_f32_e32 v104, v104, v88
	v_mul_f32_e32 v105, v105, v89
	v_mul_f32_e32 v106, v106, v90
	v_mul_f32_e32 v107, v107, v91
	v_mul_f32_e32 v108, v108, v92
	v_mul_f32_e32 v109, v109, v93
	v_mul_f32_e32 v110, v110, v94
	v_mul_f32_e32 v111, v111, v95
	v_mul_f32_e32 v104, v80, v104
	v_mul_f32_e32 v105, v81, v105
	v_mul_f32_e32 v106, v82, v106
	v_mul_f32_e32 v107, v83, v107
	v_mul_f32_e32 v108, v84, v108
	v_mul_f32_e32 v109, v85, v109
	v_mul_f32_e32 v110, v86, v110
	v_mul_f32_e32 v111, v87, v111
	v_cvt_pk_bf16_f32 v112, v104, v105
	v_cvt_pk_bf16_f32 v113, v106, v107
	v_cvt_pk_bf16_f32 v114, v108, v109
	v_cvt_pk_bf16_f32 v115, v110, v111
	global_store_dwordx4 v27, v[112:115], s[24:25]
	s_add_u32 s24, s24, 0x2800
	s_addc_u32 s25, s25, 0
	global_load_dwordx4 v[68:71], v26, s[12:13] nt
	global_load_dwordx4 v[72:75], v26, s[14:15] nt
	global_load_dwordx4 v[76:79], v26, s[96:97] nt
	s_add_u32 s12, s12, 0x800
	s_addc_u32 s13, s13, 0
	s_add_u32 s14, s14, 0x800
	s_addc_u32 s15, s15, 0
	s_add_u32 s96, s96, 0x2800
	s_addc_u32 s97, s97, 0
	s_waitcnt vmcnt(12)
	v_lshlrev_b32_e32 v80, 16, v32
	v_and_b32_e32 v81, 0xffff0000, v32
	v_lshlrev_b32_e32 v82, 16, v33
	v_and_b32_e32 v83, 0xffff0000, v33
	v_lshlrev_b32_e32 v84, 16, v34
	v_and_b32_e32 v85, 0xffff0000, v34
	v_lshlrev_b32_e32 v86, 16, v35
	v_and_b32_e32 v87, 0xffff0000, v35
	v_lshlrev_b32_e32 v96, 16, v36
	v_and_b32_e32 v97, 0xffff0000, v36
	v_lshlrev_b32_e32 v98, 16, v37
	v_and_b32_e32 v99, 0xffff0000, v37
	v_lshlrev_b32_e32 v100, 16, v38
	v_and_b32_e32 v101, 0xffff0000, v38
	v_lshlrev_b32_e32 v102, 16, v39
	v_and_b32_e32 v103, 0xffff0000, v39
	v_lshlrev_b32_e32 v88, 16, v40
	v_and_b32_e32 v89, 0xffff0000, v40
	v_lshlrev_b32_e32 v90, 16, v41
	v_and_b32_e32 v91, 0xffff0000, v41
	v_lshlrev_b32_e32 v92, 16, v42
	v_and_b32_e32 v93, 0xffff0000, v42
	v_lshlrev_b32_e32 v94, 16, v43
	v_and_b32_e32 v95, 0xffff0000, v43
	v_fmac_f32_e32 v80, v96, v18
	v_fmac_f32_e32 v81, v97, v19
	v_fmac_f32_e32 v82, v98, v20
	v_fmac_f32_e32 v83, v99, v21
	v_fmac_f32_e32 v84, v100, v22
	v_fmac_f32_e32 v85, v101, v23
	v_fmac_f32_e32 v86, v102, v24
	v_fmac_f32_e32 v87, v103, v25
	v_mul_f32_e32 v104, 0x3d372713, v88
	v_mul_f32_e32 v105, 0x3d372713, v89
	v_mul_f32_e32 v106, 0x3d372713, v90
	v_mul_f32_e32 v107, 0x3d372713, v91
	v_mul_f32_e32 v108, 0x3d372713, v92
	v_mul_f32_e32 v109, 0x3d372713, v93
	v_mul_f32_e32 v110, 0x3d372713, v94
	v_mul_f32_e32 v111, 0x3d372713, v95
	v_mul_f32_e32 v104, v104, v88
	v_mul_f32_e32 v105, v105, v89
	v_mul_f32_e32 v106, v106, v90
	v_mul_f32_e32 v107, v107, v91
	v_mul_f32_e32 v108, v108, v92
	v_mul_f32_e32 v109, v109, v93
	v_mul_f32_e32 v110, v110, v94
	v_mul_f32_e32 v111, v111, v95
	v_fma_f32 v104, v104, v88, v88
	v_fma_f32 v105, v105, v89, v89
	v_fma_f32 v106, v106, v90, v90
	v_fma_f32 v107, v107, v91, v91
	v_fma_f32 v108, v108, v92, v92
	v_fma_f32 v109, v109, v93, v93
	v_fma_f32 v110, v110, v94, v94
	v_fma_f32 v111, v111, v95, v95
	v_mul_f32_e32 v104, 0x3fcc422a, v104
	v_mul_f32_e32 v105, 0x3fcc422a, v105
	v_mul_f32_e32 v106, 0x3fcc422a, v106
	v_mul_f32_e32 v107, 0x3fcc422a, v107
	v_mul_f32_e32 v108, 0x3fcc422a, v108
	v_mul_f32_e32 v109, 0x3fcc422a, v109
	v_mul_f32_e32 v110, 0x3fcc422a, v110
	v_mul_f32_e32 v111, 0x3fcc422a, v111
	v_mul_f32_e32 v104, 0xbfb8aa3b, v104
	v_mul_f32_e32 v105, 0xbfb8aa3b, v105
	v_mul_f32_e32 v106, 0xbfb8aa3b, v106
	v_mul_f32_e32 v107, 0xbfb8aa3b, v107
	v_mul_f32_e32 v108, 0xbfb8aa3b, v108
	v_mul_f32_e32 v109, 0xbfb8aa3b, v109
	v_mul_f32_e32 v110, 0xbfb8aa3b, v110
	v_mul_f32_e32 v111, 0xbfb8aa3b, v111
	v_exp_f32_e32 v104, v104
	v_exp_f32_e32 v105, v105
	v_exp_f32_e32 v106, v106
	v_exp_f32_e32 v107, v107
	v_exp_f32_e32 v108, v108
	v_exp_f32_e32 v109, v109
	v_exp_f32_e32 v110, v110
	v_exp_f32_e32 v111, v111
	v_add_f32_e32 v104, 1.0, v104
	v_add_f32_e32 v105, 1.0, v105
	v_add_f32_e32 v106, 1.0, v106
	v_add_f32_e32 v107, 1.0, v107
	v_add_f32_e32 v108, 1.0, v108
	v_add_f32_e32 v109, 1.0, v109
	v_add_f32_e32 v110, 1.0, v110
	v_add_f32_e32 v111, 1.0, v111
	v_rcp_f32_e32 v104, v104
	v_rcp_f32_e32 v105, v105
	v_rcp_f32_e32 v106, v106
	v_rcp_f32_e32 v107, v107
	v_rcp_f32_e32 v108, v108
	v_rcp_f32_e32 v109, v109
	v_rcp_f32_e32 v110, v110
	v_rcp_f32_e32 v111, v111
	v_mul_f32_e32 v104, v104, v88
	v_mul_f32_e32 v105, v105, v89
	v_mul_f32_e32 v106, v106, v90
	v_mul_f32_e32 v107, v107, v91
	v_mul_f32_e32 v108, v108, v92
	v_mul_f32_e32 v109, v109, v93
	v_mul_f32_e32 v110, v110, v94
	v_mul_f32_e32 v111, v111, v95
	v_mul_f32_e32 v104, v80, v104
	v_mul_f32_e32 v105, v81, v105
	v_mul_f32_e32 v106, v82, v106
	v_mul_f32_e32 v107, v83, v107
	v_mul_f32_e32 v108, v84, v108
	v_mul_f32_e32 v109, v85, v109
	v_mul_f32_e32 v110, v86, v110
	v_mul_f32_e32 v111, v87, v111
	v_cvt_pk_bf16_f32 v112, v104, v105
	v_cvt_pk_bf16_f32 v113, v106, v107
	v_cvt_pk_bf16_f32 v114, v108, v109
	v_cvt_pk_bf16_f32 v115, v110, v111
	global_store_dwordx4 v27, v[112:115], s[24:25]
	s_add_u32 s24, s24, 0x2800
	s_addc_u32 s25, s25, 0
	s_waitcnt vmcnt(9)
; __device__ __forceinline__ u32x4 pack8(const float (&f)[8]) { u32x4 o; o.x = cvt_pk_bf16(f[0], f[1]); o.y = cvt_pk_bf16(f[2], f[3]); o.z = cvt_pk_bf16(f[4], f[5]); o.w = cvt_pk_bf16(f[6], f[7]); return o; }
; __device__ __forceinline__ float gelu_tanh(float x) { return x * sigmoidf_(1.5957691216057308f * (x + 0.044715f * x * x * x)); }
; __device__ __forceinline__ void fixup_phase(KP p, int l) {
;     ...
;         for (int i = 0; i < 16; ++i) {
;             const size_t m = (size_t)(m0 + i);
;             float hl[8], pc[8], gr[8], o[8], h[8];
;             unpack8(__builtin_nontemporal_load((const u32x4*)(HLOC + m * D + c0)), hl); unpack8(__builtin_nontemporal_load((const u32x4*)(PCUM + m * D + c0)), pc);
;             bf16_t* gp = P + m * DP + C_GR + c0; unpack8(*(const u32x4*)gp, gr);
; #pragma unroll
;             for (int e = 0; e < 8; ++e) { h[e] = hl[e] + pc[e] * carry[e]; o[e] = gelu_tanh(gr[e]) * h[e]; }
;             *(u32x4*)gp = pack8(o);
	v_lshlrev_b32_e32 v80, 16, v44
	v_and_b32_e32 v81, 0xffff0000, v44
	v_lshlrev_b32_e32 v82, 16, v45
	v_and_b32_e32 v83, 0xffff0000, v45
	v_lshlrev_b32_e32 v84, 16, v46
	v_and_b32_e32 v85, 0xffff0000, v46
	v_lshlrev_b32_e32 v86, 16, v47
	v_and_b32_e32 v87, 0xffff0000, v47
	v_lshlrev_b32_e32 v96, 16, v48
	v_and_b32_e32 v97, 0xffff0000, v48
	v_lshlrev_b32_e32 v98, 16, v49
	v_and_b32_e32 v99, 0xffff0000, v49
	v_lshlrev_b32_e32 v100, 16, v50
	v_and_b32_e32 v101, 0xffff0000, v50
	v_lshlrev_b32_e32 v102, 16, v51
	v_and_b32_e32 v103, 0xffff0000, v51
	v_lshlrev_b32_e32 v88, 16, v52
	v_and_b32_e32 v89, 0xffff0000, v52
	v_lshlrev_b32_e32 v90, 16, v53
	v_and_b32_e32 v91, 0xffff0000, v53
	v_lshlrev_b32_e32 v92, 16, v54
	v_and_b32_e32 v93, 0xffff0000, v54
	v_lshlrev_b32_e32 v94, 16, v55
	v_and_b32_e32 v95, 0xffff0000, v55
	v_fmac_f32_e32 v80, v96, v18
	v_fmac_f32_e32 v81, v97, v19
	v_fmac_f32_e32 v82, v98, v20
	v_fmac_f32_e32 v83, v99, v21
	v_fmac_f32_e32 v84, v100, v22
	v_fmac_f32_e32 v85, v101, v23
	v_fmac_f32_e32 v86, v102, v24
	v_fmac_f32_e32 v87, v103, v25
	v_mul_f32_e32 v104, 0x3d372713, v88
	v_mul_f32_e32 v105, 0x3d372713, v89
	v_mul_f32_e32 v106, 0x3d372713, v90
	v_mul_f32_e32 v107, 0x3d372713, v91
	v_mul_f32_e32 v108, 0x3d372713, v92
	v_mul_f32_e32 v109, 0x3d372713, v93
	v_mul_f32_e32 v110, 0x3d372713, v94
	v_mul_f32_e32 v111, 0x3d372713, v95
	v_mul_f32_e32 v104, v104, v88
	v_mul_f32_e32 v105, v105, v89
	v_mul_f32_e32 v106, v106, v90
	v_mul_f32_e32 v107, v107, v91
	v_mul_f32_e32 v108, v108, v92
	v_mul_f32_e32 v109, v109, v93
	v_mul_f32_e32 v110, v110, v94
	v_mul_f32_e32 v111, v111, v95
	v_fma_f32 v104, v104, v88, v88
	v_fma_f32 v105, v105, v89, v89
	v_fma_f32 v106, v106, v90, v90
	v_fma_f32 v107, v107, v91, v91
	v_fma_f32 v108, v108, v92, v92
	v_fma_f32 v109, v109, v93, v93
	v_fma_f32 v110, v110, v94, v94
	v_fma_f32 v111, v111, v95, v95
	v_mul_f32_e32 v104, 0x3fcc422a, v104
	v_mul_f32_e32 v105, 0x3fcc422a, v105
	v_mul_f32_e32 v106, 0x3fcc422a, v106
	v_mul_f32_e32 v107, 0x3fcc422a, v107
	v_mul_f32_e32 v108, 0x3fcc422a, v108
	v_mul_f32_e32 v109, 0x3fcc422a, v109
	v_mul_f32_e32 v110, 0x3fcc422a, v110
	v_mul_f32_e32 v111, 0x3fcc422a, v111
	v_mul_f32_e32 v104, 0xbfb8aa3b, v104
	v_mul_f32_e32 v105, 0xbfb8aa3b, v105
	v_mul_f32_e32 v106, 0xbfb8aa3b, v106
	v_mul_f32_e32 v107, 0xbfb8aa3b, v107
	v_mul_f32_e32 v108, 0xbfb8aa3b, v108
	v_mul_f32_e32 v109, 0xbfb8aa3b, v109
	v_mul_f32_e32 v110, 0xbfb8aa3b, v110
	v_mul_f32_e32 v111, 0xbfb8aa3b, v111
	v_exp_f32_e32 v104, v104
	v_exp_f32_e32 v105, v105
	v_exp_f32_e32 v106, v106
	v_exp_f32_e32 v107, v107
	v_exp_f32_e32 v108, v108
	v_exp_f32_e32 v109, v109
	v_exp_f32_e32 v110, v110
	v_exp_f32_e32 v111, v111
	v_add_f32_e32 v104, 1.0, v104
	v_add_f32_e32 v105, 1.0, v105
	v_add_f32_e32 v106, 1.0, v106
	v_add_f32_e32 v107, 1.0, v107
	v_add_f32_e32 v108, 1.0, v108
	v_add_f32_e32 v109, 1.0, v109
	v_add_f32_e32 v110, 1.0, v110
	v_add_f32_e32 v111, 1.0, v111
	v_rcp_f32_e32 v104, v104
	v_rcp_f32_e32 v105, v105
	v_rcp_f32_e32 v106, v106
	v_rcp_f32_e32 v107, v107
	v_rcp_f32_e32 v108, v108
	v_rcp_f32_e32 v109, v109
	v_rcp_f32_e32 v110, v110
	v_rcp_f32_e32 v111, v111
	v_mul_f32_e32 v104, v104, v88
	v_mul_f32_e32 v105, v105, v89
	v_mul_f32_e32 v106, v106, v90
	v_mul_f32_e32 v107, v107, v91
	v_mul_f32_e32 v108, v108, v92
	v_mul_f32_e32 v109, v109, v93
	v_mul_f32_e32 v110, v110, v94
	v_mul_f32_e32 v111, v111, v95
	v_mul_f32_e32 v104, v80, v104
	v_mul_f32_e32 v105, v81, v105
	v_mul_f32_e32 v106, v82, v106
	v_mul_f32_e32 v107, v83, v107
	v_mul_f32_e32 v108, v84, v108
	v_mul_f32_e32 v109, v85, v109
	v_mul_f32_e32 v110, v86, v110
	v_mul_f32_e32 v111, v87, v111
	v_cvt_pk_bf16_f32 v112, v104, v105
	v_cvt_pk_bf16_f32 v113, v106, v107
	v_cvt_pk_bf16_f32 v114, v108, v109
	v_cvt_pk_bf16_f32 v115, v110, v111
	global_store_dwordx4 v27, v[112:115], s[24:25]
	s_add_u32 s24, s24, 0x2800
	s_addc_u32 s25, s25, 0
	s_waitcnt vmcnt(6)
	v_lshlrev_b32_e32 v80, 16, v56
	v_and_b32_e32 v81, 0xffff0000, v56
	v_lshlrev_b32_e32 v82, 16, v57
	v_and_b32_e32 v83, 0xffff0000, v57
	v_lshlrev_b32_e32 v84, 16, v58
	v_and_b32_e32 v85, 0xffff0000, v58
	v_lshlrev_b32_e32 v86, 16, v59
	v_and_b32_e32 v87, 0xffff0000, v59
	v_lshlrev_b32_e32 v96, 16, v60
	v_and_b32_e32 v97, 0xffff0000, v60
	v_lshlrev_b32_e32 v98, 16, v61
	v_and_b32_e32 v99, 0xffff0000, v61
	v_lshlrev_b32_e32 v100, 16, v62
	v_and_b32_e32 v101, 0xffff0000, v62
	v_lshlrev_b32_e32 v102, 16, v63
	v_and_b32_e32 v103, 0xffff0000, v63
	v_lshlrev_b32_e32 v88, 16, v64
	v_and_b32_e32 v89, 0xffff0000, v64
	v_lshlrev_b32_e32 v90, 16, v65
	v_and_b32_e32 v91, 0xffff0000, v65
	v_lshlrev_b32_e32 v92, 16, v66
	v_and_b32_e32 v93, 0xffff0000, v66
	v_lshlrev_b32_e32 v94, 16, v67
	v_and_b32_e32 v95, 0xffff0000, v67
	v_fmac_f32_e32 v80, v96, v18
	v_fmac_f32_e32 v81, v97, v19
	v_fmac_f32_e32 v82, v98, v20
	v_fmac_f32_e32 v83, v99, v21
	v_fmac_f32_e32 v84, v100, v22
	v_fmac_f32_e32 v85, v101, v23
	v_fmac_f32_e32 v86, v102, v24
	v_fmac_f32_e32 v87, v103, v25
	v_mul_f32_e32 v104, 0x3d372713, v88
	v_mul_f32_e32 v105, 0x3d372713, v89
	v_mul_f32_e32 v106, 0x3d372713, v90
	v_mul_f32_e32 v107, 0x3d372713, v91
	v_mul_f32_e32 v108, 0x3d372713, v92
	v_mul_f32_e32 v109, 0x3d372713, v93
	v_mul_f32_e32 v110, 0x3d372713, v94
	v_mul_f32_e32 v111, 0x3d372713, v95
	v_mul_f32_e32 v104, v104, v88
	v_mul_f32_e32 v105, v105, v89
	v_mul_f32_e32 v106, v106, v90
	v_mul_f32_e32 v107, v107, v91
	v_mul_f32_e32 v108, v108, v92
	v_mul_f32_e32 v109, v109, v93
	v_mul_f32_e32 v110, v110, v94
	v_mul_f32_e32 v111, v111, v95
	v_fma_f32 v104, v104, v88, v88
	v_fma_f32 v105, v105, v89, v89
	v_fma_f32 v106, v106, v90, v90
	v_fma_f32 v107, v107, v91, v91
; __device__ __forceinline__ u32x4 pack8(const float (&f)[8]) { u32x4 o; o.x = cvt_pk_bf16(f[0], f[1]); o.y = cvt_pk_bf16(f[2], f[3]); o.z = cvt_pk_bf16(f[4], f[5]); o.w = cvt_pk_bf16(f[6], f[7]); return o; }
; __device__ __forceinline__ float gelu_tanh(float x) { return x * sigmoidf_(1.5957691216057308f * (x + 0.044715f * x * x * x)); }
; __device__ __forceinline__ void fixup_phase(KP p, int l) {
;     ...
;         for (int i = 0; i < 16; ++i) {
;             const size_t m = (size_t)(m0 + i);
;             float hl[8], pc[8], gr[8], o[8], h[8];
;             unpack8(__builtin_nontemporal_load((const u32x4*)(HLOC + m * D + c0)), hl); unpack8(__builtin_nontemporal_load((const u32x4*)(PCUM + m * D + c0)), pc);
;             bf16_t* gp = P + m * DP + C_GR + c0; unpack8(*(const u32x4*)gp, gr);
; #pragma unroll
;             for (int e = 0; e < 8; ++e) { h[e] = hl[e] + pc[e] * carry[e]; o[e] = gelu_tanh(gr[e]) * h[e]; }
;             *(u32x4*)gp = pack8(o);
;             if (tile < 1032 && t0 + i == TP - 1) store8f(p->out + O_PRG + (size_t)(l * NB + b) * D + c0, h);
	v_fma_f32 v108, v108, v92, v92
	v_fma_f32 v109, v109, v93, v93
	v_fma_f32 v110, v110, v94, v94
	v_fma_f32 v111, v111, v95, v95
	v_mul_f32_e32 v104, 0x3fcc422a, v104
	v_mul_f32_e32 v105, 0x3fcc422a, v105
	v_mul_f32_e32 v106, 0x3fcc422a, v106
	v_mul_f32_e32 v107, 0x3fcc422a, v107
	v_mul_f32_e32 v108, 0x3fcc422a, v108
	v_mul_f32_e32 v109, 0x3fcc422a, v109
	v_mul_f32_e32 v110, 0x3fcc422a, v110
	v_mul_f32_e32 v111, 0x3fcc422a, v111
	v_mul_f32_e32 v104, 0xbfb8aa3b, v104
	v_mul_f32_e32 v105, 0xbfb8aa3b, v105
	v_mul_f32_e32 v106, 0xbfb8aa3b, v106
	v_mul_f32_e32 v107, 0xbfb8aa3b, v107
	v_mul_f32_e32 v108, 0xbfb8aa3b, v108
	v_mul_f32_e32 v109, 0xbfb8aa3b, v109
	v_mul_f32_e32 v110, 0xbfb8aa3b, v110
	v_mul_f32_e32 v111, 0xbfb8aa3b, v111
	v_exp_f32_e32 v104, v104
	v_exp_f32_e32 v105, v105
	v_exp_f32_e32 v106, v106
	v_exp_f32_e32 v107, v107
	v_exp_f32_e32 v108, v108
	v_exp_f32_e32 v109, v109
	v_exp_f32_e32 v110, v110
	v_exp_f32_e32 v111, v111
	v_add_f32_e32 v104, 1.0, v104
	v_add_f32_e32 v105, 1.0, v105
	v_add_f32_e32 v106, 1.0, v106
	v_add_f32_e32 v107, 1.0, v107
	v_add_f32_e32 v108, 1.0, v108
	v_add_f32_e32 v109, 1.0, v109
	v_add_f32_e32 v110, 1.0, v110
	v_add_f32_e32 v111, 1.0, v111
	v_rcp_f32_e32 v104, v104
	v_rcp_f32_e32 v105, v105
	v_rcp_f32_e32 v106, v106
	v_rcp_f32_e32 v107, v107
	v_rcp_f32_e32 v108, v108
	v_rcp_f32_e32 v109, v109
	v_rcp_f32_e32 v110, v110
	v_rcp_f32_e32 v111, v111
	v_mul_f32_e32 v104, v104, v88
	v_mul_f32_e32 v105, v105, v89
	v_mul_f32_e32 v106, v106, v90
	v_mul_f32_e32 v107, v107, v91
	v_mul_f32_e32 v108, v108, v92
	v_mul_f32_e32 v109, v109, v93
	v_mul_f32_e32 v110, v110, v94
	v_mul_f32_e32 v111, v111, v95
	v_mul_f32_e32 v104, v80, v104
	v_mul_f32_e32 v105, v81, v105
	v_mul_f32_e32 v106, v82, v106
	v_mul_f32_e32 v107, v83, v107
	v_mul_f32_e32 v108, v84, v108
	v_mul_f32_e32 v109, v85, v109
	v_mul_f32_e32 v110, v86, v110
	v_mul_f32_e32 v111, v87, v111
	v_cvt_pk_bf16_f32 v112, v104, v105
	v_cvt_pk_bf16_f32 v113, v106, v107
	v_cvt_pk_bf16_f32 v114, v108, v109
	v_cvt_pk_bf16_f32 v115, v110, v111
	global_store_dwordx4 v27, v[112:115], s[24:25]
	s_add_u32 s24, s24, 0x2800
	s_addc_u32 s25, s25, 0
	s_waitcnt vmcnt(3)
	v_lshlrev_b32_e32 v80, 16, v68
	v_and_b32_e32 v81, 0xffff0000, v68
	v_lshlrev_b32_e32 v82, 16, v69
	v_and_b32_e32 v83, 0xffff0000, v69
	v_lshlrev_b32_e32 v84, 16, v70
	v_and_b32_e32 v85, 0xffff0000, v70
	v_lshlrev_b32_e32 v86, 16, v71
	v_and_b32_e32 v87, 0xffff0000, v71
	v_lshlrev_b32_e32 v96, 16, v72
	v_and_b32_e32 v97, 0xffff0000, v72
	v_lshlrev_b32_e32 v98, 16, v73
	v_and_b32_e32 v99, 0xffff0000, v73
	v_lshlrev_b32_e32 v100, 16, v74
	v_and_b32_e32 v101, 0xffff0000, v74
	v_lshlrev_b32_e32 v102, 16, v75
	v_and_b32_e32 v103, 0xffff0000, v75
	v_lshlrev_b32_e32 v88, 16, v76
	v_and_b32_e32 v89, 0xffff0000, v76
	v_lshlrev_b32_e32 v90, 16, v77
	v_and_b32_e32 v91, 0xffff0000, v77
	v_lshlrev_b32_e32 v92, 16, v78
	v_and_b32_e32 v93, 0xffff0000, v78
	v_lshlrev_b32_e32 v94, 16, v79
	v_and_b32_e32 v95, 0xffff0000, v79
	v_fmac_f32_e32 v80, v96, v18
	v_fmac_f32_e32 v81, v97, v19
	v_fmac_f32_e32 v82, v98, v20
	v_fmac_f32_e32 v83, v99, v21
	v_fmac_f32_e32 v84, v100, v22
	v_fmac_f32_e32 v85, v101, v23
	v_fmac_f32_e32 v86, v102, v24
	v_fmac_f32_e32 v87, v103, v25
	v_mul_f32_e32 v104, 0x3d372713, v88
	v_mul_f32_e32 v105, 0x3d372713, v89
	v_mul_f32_e32 v106, 0x3d372713, v90
	v_mul_f32_e32 v107, 0x3d372713, v91
	v_mul_f32_e32 v108, 0x3d372713, v92
	v_mul_f32_e32 v109, 0x3d372713, v93
	v_mul_f32_e32 v110, 0x3d372713, v94
	v_mul_f32_e32 v111, 0x3d372713, v95
	v_mul_f32_e32 v104, v104, v88
	v_mul_f32_e32 v105, v105, v89
	v_mul_f32_e32 v106, v106, v90
	v_mul_f32_e32 v107, v107, v91
	v_mul_f32_e32 v108, v108, v92
	v_mul_f32_e32 v109, v109, v93
	v_mul_f32_e32 v110, v110, v94
	v_mul_f32_e32 v111, v111, v95
	v_fma_f32 v104, v104, v88, v88
	v_fma_f32 v105, v105, v89, v89
	v_fma_f32 v106, v106, v90, v90
	v_fma_f32 v107, v107, v91, v91
	v_fma_f32 v108, v108, v92, v92
	v_fma_f32 v109, v109, v93, v93
	v_fma_f32 v110, v110, v94, v94
	v_fma_f32 v111, v111, v95, v95
	v_mul_f32_e32 v104, 0x3fcc422a, v104
	v_mul_f32_e32 v105, 0x3fcc422a, v105
	v_mul_f32_e32 v106, 0x3fcc422a, v106
	v_mul_f32_e32 v107, 0x3fcc422a, v107
	v_mul_f32_e32 v108, 0x3fcc422a, v108
	v_mul_f32_e32 v109, 0x3fcc422a, v109
	v_mul_f32_e32 v110, 0x3fcc422a, v110
	v_mul_f32_e32 v111, 0x3fcc422a, v111
	v_mul_f32_e32 v104, 0xbfb8aa3b, v104
	v_mul_f32_e32 v105, 0xbfb8aa3b, v105
	v_mul_f32_e32 v106, 0xbfb8aa3b, v106
	v_mul_f32_e32 v107, 0xbfb8aa3b, v107
	v_mul_f32_e32 v108, 0xbfb8aa3b, v108
	v_mul_f32_e32 v109, 0xbfb8aa3b, v109
	v_mul_f32_e32 v110, 0xbfb8aa3b, v110
	v_mul_f32_e32 v111, 0xbfb8aa3b, v111
	v_exp_f32_e32 v104, v104
	v_exp_f32_e32 v105, v105
	v_exp_f32_e32 v106, v106
	v_exp_f32_e32 v107, v107
	v_exp_f32_e32 v108, v108
	v_exp_f32_e32 v109, v109
	v_exp_f32_e32 v110, v110
	v_exp_f32_e32 v111, v111
	v_add_f32_e32 v104, 1.0, v104
	v_add_f32_e32 v105, 1.0, v105
	v_add_f32_e32 v106, 1.0, v106
	v_add_f32_e32 v107, 1.0, v107
	v_add_f32_e32 v108, 1.0, v108
	v_add_f32_e32 v109, 1.0, v109
	v_add_f32_e32 v110, 1.0, v110
	v_add_f32_e32 v111, 1.0, v111
	v_rcp_f32_e32 v104, v104
	v_rcp_f32_e32 v105, v105
	v_rcp_f32_e32 v106, v106
	v_rcp_f32_e32 v107, v107
	v_rcp_f32_e32 v108, v108
	v_rcp_f32_e32 v109, v109
	v_rcp_f32_e32 v110, v110
	v_rcp_f32_e32 v111, v111
	v_mul_f32_e32 v104, v104, v88
	v_mul_f32_e32 v105, v105, v89
	v_mul_f32_e32 v106, v106, v90
	v_mul_f32_e32 v107, v107, v91
	v_mul_f32_e32 v108, v108, v92
	v_mul_f32_e32 v109, v109, v93
	v_mul_f32_e32 v110, v110, v94
	v_mul_f32_e32 v111, v111, v95
	v_mul_f32_e32 v104, v80, v104
	v_mul_f32_e32 v105, v81, v105
	v_mul_f32_e32 v106, v82, v106
	v_mul_f32_e32 v107, v83, v107
	v_mul_f32_e32 v108, v84, v108
	v_mul_f32_e32 v109, v85, v109
	v_mul_f32_e32 v110, v86, v110
	v_mul_f32_e32 v111, v87, v111
	v_cvt_pk_bf16_f32 v112, v104, v105
	v_cvt_pk_bf16_f32 v113, v106, v107
	v_cvt_pk_bf16_f32 v114, v108, v109
	v_cvt_pk_bf16_f32 v115, v110, v111
	global_store_dwordx4 v27, v[112:115], s[24:25]
	s_cmp_eq_u32 s43, 0
	s_cbranch_scc1 .Lfx_noprg
	s_lshl_b32 s44, s18, 12
	s_lshl_b32 s23, s10, 12
	s_add_i32 s44, s44, s23
	s_add_u32 s98, s72, 0x4120000
	s_addc_u32 s99, s73, 0
	s_add_u32 s98, s98, s44
	s_addc_u32 s99, s99, 0
	global_store_dwordx4 v31, v[80:83], s[98:99]
	global_store_dwordx4 v31, v[84:87], s[98:99] offset:16
